# v15 + the redundant s_waitcnt lgkmcnt(0) behind each pre-MMA barrier removed (the same wait sits in front of the barrier)
# speedup vs baseline: 1.0166x; 1.0003x over previous
.Lsp_p2:
.LBB0_213:
	ds_read_b128 v[146:149], v156
	ds_read_b128 v[150:153], v156 offset:1024
	ds_read_b128 v[160:163], v156 offset:2048
	ds_read_b128 v[164:167], v156 offset:3072
	ds_read_b128 v[168:171], v157
	ds_read_b128 v[172:175], v157 offset:1024
	ds_read_b128 v[176:179], v157 offset:2048
	ds_read_b128 v[180:183], v157 offset:3072
	s_add_u32 s19, s84, 0xfff80080
	s_addc_u32 s20, s85, -1
	s_cmp_eq_u32 s18, 28
	s_cselect_b32 s89, s8, s20
	s_cselect_b32 s88, s9, s19
	s_cselect_b32 s87, s12, s17
	s_cselect_b32 s86, s13, s16
	v_lshl_add_u64 v[216:217], s[84:85], 0, v[138:139]
	s_add_i32 m0, s57, 0xc000
	ds_read_b128 v[184:187], v158
	ds_read_b128 v[188:191], v158 offset:1024
	ds_read_b128 v[192:195], v158 offset:2048
	ds_read_b128 v[196:199], v158 offset:3072
	ds_read_b128 v[200:203], v158 offset:4096
	ds_read_b128 v[204:207], v158 offset:5120
	ds_read_b128 v[208:211], v158 offset:6144
	ds_read_b128 v[212:215], v158 offset:7168
	global_load_lds_dwordx4 v[216:217], off
	v_lshl_add_u64 v[216:217], s[84:85], 0, v[140:141]
	s_add_i32 m0, s57, 0xe000
	s_nop 0
	global_load_lds_dwordx4 v[216:217], off
	s_waitcnt vmcnt(8)
	s_waitcnt lgkmcnt(0)
	s_barrier
	v_mfma_i32_16x16x64_i8 v[126:129], v[146:149], v[184:187], v[126:129]
	v_mfma_i32_16x16x64_i8 v[122:125], v[160:163], v[184:187], v[122:125]
	v_mfma_i32_16x16x64_i8 v[110:113], v[146:149], v[192:195], v[110:113]
	v_mfma_i32_16x16x64_i8 v[106:109], v[160:163], v[192:195], v[106:109]
	v_mfma_i32_16x16x64_i8 v[94:97], v[146:149], v[200:203], v[94:97]
	v_mfma_i32_16x16x64_i8 v[90:93], v[160:163], v[200:203], v[90:93]
	v_mfma_i32_16x16x64_i8 v[78:81], v[146:149], v[208:211], v[78:81]
	v_mfma_i32_16x16x64_i8 v[74:77], v[160:163], v[208:211], v[74:77]
	v_mfma_i32_16x16x64_i8 v[126:129], v[150:153], v[188:191], v[126:129]
	v_mfma_i32_16x16x64_i8 v[122:125], v[164:167], v[188:191], v[122:125]
	v_mfma_i32_16x16x64_i8 v[110:113], v[150:153], v[196:199], v[110:113]
	v_mfma_i32_16x16x64_i8 v[106:109], v[164:167], v[196:199], v[106:109]
	v_mfma_i32_16x16x64_i8 v[94:97], v[150:153], v[204:207], v[94:97]
	v_mfma_i32_16x16x64_i8 v[90:93], v[164:167], v[204:207], v[90:93]
	v_mfma_i32_16x16x64_i8 v[78:81], v[150:153], v[212:215], v[78:81]
	v_mfma_i32_16x16x64_i8 v[74:77], v[164:167], v[212:215], v[74:77]
	v_mfma_i32_16x16x64_i8 v[118:121], v[168:171], v[184:187], v[118:121]
	v_mfma_i32_16x16x64_i8 v[114:117], v[176:179], v[184:187], v[114:117]
	v_mfma_i32_16x16x64_i8 v[102:105], v[168:171], v[192:195], v[102:105]
	v_mfma_i32_16x16x64_i8 v[98:101], v[176:179], v[192:195], v[98:101]
	v_mfma_i32_16x16x64_i8 v[86:89], v[168:171], v[200:203], v[86:89]
	v_mfma_i32_16x16x64_i8 v[82:85], v[176:179], v[200:203], v[82:85]
	v_mfma_i32_16x16x64_i8 v[70:73], v[168:171], v[208:211], v[70:73]
	v_mfma_i32_16x16x64_i8 v[66:69], v[176:179], v[208:211], v[66:69]
	v_mfma_i32_16x16x64_i8 v[118:121], v[172:175], v[188:191], v[118:121]
	v_mfma_i32_16x16x64_i8 v[114:117], v[180:183], v[188:191], v[114:117]
	v_mfma_i32_16x16x64_i8 v[102:105], v[172:175], v[196:199], v[102:105]
	v_mfma_i32_16x16x64_i8 v[98:101], v[180:183], v[196:199], v[98:101]
	v_mfma_i32_16x16x64_i8 v[86:89], v[172:175], v[204:207], v[86:89]
	v_mfma_i32_16x16x64_i8 v[82:85], v[180:183], v[204:207], v[82:85]
	v_mfma_i32_16x16x64_i8 v[70:73], v[172:175], v[212:215], v[70:73]
	v_mfma_i32_16x16x64_i8 v[66:69], v[180:183], v[212:215], v[66:69]
	s_barrier
	s_add_i32 s19, s83, s35
	v_lshl_add_u64 v[216:217], s[86:87], 0, v[134:135]
	s_mov_b32 m0, s19
	ds_read_b128 v[184:187], v158 offset:16384
	ds_read_b128 v[188:191], v158 offset:17408
	ds_read_b128 v[192:195], v158 offset:18432
	ds_read_b128 v[196:199], v158 offset:19456
	ds_read_b128 v[200:203], v158 offset:20480
	ds_read_b128 v[204:207], v158 offset:21504
	ds_read_b128 v[208:211], v158 offset:22528
	ds_read_b128 v[212:215], v158 offset:23552
	global_load_lds_dwordx4 v[216:217], off
	s_add_i32 m0, s19, 0x2000
	s_add_u32 s20, s86, 0x80000
	v_lshl_add_u64 v[218:219], s[86:87], 0, v[130:131]
	s_addc_u32 s21, s87, 0
	s_add_i32 s19, s90, s35
	global_load_lds_dwordx4 v[218:219], off
	v_lshl_add_u64 v[220:221], s[20:21], 0, v[134:135]
	s_mov_b32 m0, s19
	v_lshl_add_u64 v[222:223], s[88:89], 0, v[132:133]
	global_load_lds_dwordx4 v[220:221], off
	v_lshl_add_u64 v[220:221], s[20:21], 0, v[130:131]
	s_add_i32 m0, s19, 0x2000
	s_nop 0
	global_load_lds_dwordx4 v[220:221], off
	v_lshl_add_u64 v[220:221], s[88:89], 0, v[136:137]
	s_mov_b32 m0, s57
	s_nop 0
	global_load_lds_dwordx4 v[220:221], off
	s_mov_b32 m0, s58
	s_nop 0
	global_load_lds_dwordx4 v[222:223], off
	s_waitcnt vmcnt(8)
	s_waitcnt lgkmcnt(0)
	s_barrier
	v_mfma_i32_16x16x64_i8 v[62:65], v[146:149], v[184:187], v[62:65]
	v_mfma_i32_16x16x64_i8 v[58:61], v[160:163], v[184:187], v[58:61]
	v_mfma_i32_16x16x64_i8 v[46:49], v[146:149], v[192:195], v[46:49]
	v_mfma_i32_16x16x64_i8 v[42:45], v[160:163], v[192:195], v[42:45]
	v_mfma_i32_16x16x64_i8 v[30:33], v[146:149], v[200:203], v[30:33]
	v_mfma_i32_16x16x64_i8 v[26:29], v[160:163], v[200:203], v[26:29]
	v_mfma_i32_16x16x64_i8 v[14:17], v[146:149], v[208:211], v[14:17]
	v_mfma_i32_16x16x64_i8 v[10:13], v[160:163], v[208:211], v[10:13]
	v_mfma_i32_16x16x64_i8 v[62:65], v[150:153], v[188:191], v[62:65]
	v_mfma_i32_16x16x64_i8 v[58:61], v[164:167], v[188:191], v[58:61]
	v_mfma_i32_16x16x64_i8 v[46:49], v[150:153], v[196:199], v[46:49]
	v_mfma_i32_16x16x64_i8 v[42:45], v[164:167], v[196:199], v[42:45]
	v_mfma_i32_16x16x64_i8 v[30:33], v[150:153], v[204:207], v[30:33]
	v_mfma_i32_16x16x64_i8 v[26:29], v[164:167], v[204:207], v[26:29]
	v_mfma_i32_16x16x64_i8 v[14:17], v[150:153], v[212:215], v[14:17]
	v_mfma_i32_16x16x64_i8 v[10:13], v[164:167], v[212:215], v[10:13]
	v_mfma_i32_16x16x64_i8 v[54:57], v[168:171], v[184:187], v[54:57]
	v_mfma_i32_16x16x64_i8 v[50:53], v[176:179], v[184:187], v[50:53]
	v_mfma_i32_16x16x64_i8 v[38:41], v[168:171], v[192:195], v[38:41]
	v_mfma_i32_16x16x64_i8 v[34:37], v[176:179], v[192:195], v[34:37]
	v_mfma_i32_16x16x64_i8 v[22:25], v[168:171], v[200:203], v[22:25]
	v_mfma_i32_16x16x64_i8 v[18:21], v[176:179], v[200:203], v[18:21]
	v_mfma_i32_16x16x64_i8 v[6:9], v[168:171], v[208:211], v[6:9]
	v_mfma_i32_16x16x64_i8 v[2:5], v[176:179], v[208:211], v[2:5]
	v_mfma_i32_16x16x64_i8 v[54:57], v[172:175], v[188:191], v[54:57]
	v_mfma_i32_16x16x64_i8 v[50:53], v[180:183], v[188:191], v[50:53]
	v_mfma_i32_16x16x64_i8 v[38:41], v[172:175], v[196:199], v[38:41]
	v_mfma_i32_16x16x64_i8 v[34:37], v[180:183], v[196:199], v[34:37]
	v_mfma_i32_16x16x64_i8 v[22:25], v[172:175], v[204:207], v[22:25]
	v_mfma_i32_16x16x64_i8 v[18:21], v[180:183], v[204:207], v[18:21]
	v_mfma_i32_16x16x64_i8 v[6:9], v[172:175], v[212:215], v[6:9]
	v_mfma_i32_16x16x64_i8 v[2:5], v[180:183], v[212:215], v[2:5]
	s_barrier
	s_add_i32 s19, 0, 0x18000
	v_add_u32_e32 v159, s19, v154
	s_add_i32 s22, 0, 0x1c000
	ds_read_b128 v[146:149], v159
	ds_read_b128 v[150:153], v159 offset:1024
	ds_read_b128 v[160:163], v159 offset:2048
	ds_read_b128 v[164:167], v159 offset:3072
	v_add_u32_e32 v159, s22, v154
	ds_read_b128 v[168:171], v159
	ds_read_b128 v[172:175], v159 offset:1024
	ds_read_b128 v[176:179], v159 offset:2048
	ds_read_b128 v[180:183], v159 offset:3072
	s_add_u32 s20, s88, 0x80000
	s_addc_u32 s21, s89, 0
	s_mov_b32 m0, s59
	v_lshl_add_u64 v[224:225], s[20:21], 0, v[136:137]
	ds_read_b128 v[184:187], v158 offset:32768
	ds_read_b128 v[188:191], v158 offset:33792
	ds_read_b128 v[192:195], v158 offset:34816
	ds_read_b128 v[196:199], v158 offset:35840
	ds_read_b128 v[200:203], v158 offset:36864
	ds_read_b128 v[204:207], v158 offset:37888
	ds_read_b128 v[208:211], v158 offset:38912
	ds_read_b128 v[212:215], v158 offset:39936
	global_load_lds_dwordx4 v[224:225], off
	v_lshl_add_u64 v[224:225], s[20:21], 0, v[132:133]
	s_mov_b32 m0, s61
	s_nop 0
	global_load_lds_dwordx4 v[224:225], off
	s_waitcnt vmcnt(8)
	s_waitcnt lgkmcnt(0)
	s_barrier
	v_mfma_i32_16x16x64_i8 v[126:129], v[146:149], v[184:187], v[126:129]
	v_mfma_i32_16x16x64_i8 v[122:125], v[160:163], v[184:187], v[122:125]
	v_mfma_i32_16x16x64_i8 v[110:113], v[146:149], v[192:195], v[110:113]
	v_mfma_i32_16x16x64_i8 v[106:109], v[160:163], v[192:195], v[106:109]
	v_mfma_i32_16x16x64_i8 v[94:97], v[146:149], v[200:203], v[94:97]
	v_mfma_i32_16x16x64_i8 v[90:93], v[160:163], v[200:203], v[90:93]
	v_mfma_i32_16x16x64_i8 v[78:81], v[146:149], v[208:211], v[78:81]
	v_mfma_i32_16x16x64_i8 v[74:77], v[160:163], v[208:211], v[74:77]
	v_mfma_i32_16x16x64_i8 v[126:129], v[150:153], v[188:191], v[126:129]
	v_mfma_i32_16x16x64_i8 v[122:125], v[164:167], v[188:191], v[122:125]
	v_mfma_i32_16x16x64_i8 v[110:113], v[150:153], v[196:199], v[110:113]
	v_mfma_i32_16x16x64_i8 v[106:109], v[164:167], v[196:199], v[106:109]
	v_mfma_i32_16x16x64_i8 v[94:97], v[150:153], v[204:207], v[94:97]
	v_mfma_i32_16x16x64_i8 v[90:93], v[164:167], v[204:207], v[90:93]
	v_mfma_i32_16x16x64_i8 v[78:81], v[150:153], v[212:215], v[78:81]
	v_mfma_i32_16x16x64_i8 v[74:77], v[164:167], v[212:215], v[74:77]
	v_mfma_i32_16x16x64_i8 v[118:121], v[168:171], v[184:187], v[118:121]
	v_mfma_i32_16x16x64_i8 v[114:117], v[176:179], v[184:187], v[114:117]
	v_mfma_i32_16x16x64_i8 v[102:105], v[168:171], v[192:195], v[102:105]
	v_mfma_i32_16x16x64_i8 v[98:101], v[176:179], v[192:195], v[98:101]
	v_mfma_i32_16x16x64_i8 v[86:89], v[168:171], v[200:203], v[86:89]
	v_mfma_i32_16x16x64_i8 v[82:85], v[176:179], v[200:203], v[82:85]
	v_mfma_i32_16x16x64_i8 v[70:73], v[168:171], v[208:211], v[70:73]
	v_mfma_i32_16x16x64_i8 v[66:69], v[176:179], v[208:211], v[66:69]
	v_mfma_i32_16x16x64_i8 v[118:121], v[172:175], v[188:191], v[118:121]
	v_mfma_i32_16x16x64_i8 v[114:117], v[180:183], v[188:191], v[114:117]
	v_mfma_i32_16x16x64_i8 v[102:105], v[172:175], v[196:199], v[102:105]
	v_mfma_i32_16x16x64_i8 v[98:101], v[180:183], v[196:199], v[98:101]
	v_mfma_i32_16x16x64_i8 v[86:89], v[172:175], v[204:207], v[86:89]
	v_mfma_i32_16x16x64_i8 v[82:85], v[180:183], v[204:207], v[82:85]
	v_mfma_i32_16x16x64_i8 v[70:73], v[172:175], v[212:215], v[70:73]
	v_mfma_i32_16x16x64_i8 v[66:69], v[180:183], v[212:215], v[66:69]
	s_barrier
	s_add_i32 s19, s19, s35
	v_lshl_add_u64 v[216:217], v[216:217], 0, s[4:5]
	s_mov_b32 m0, s19
	ds_read_b128 v[184:187], v158 offset:49152
	ds_read_b128 v[188:191], v158 offset:50176
	ds_read_b128 v[192:195], v158 offset:51200
	ds_read_b128 v[196:199], v158 offset:52224
	ds_read_b128 v[200:203], v158 offset:53248
	ds_read_b128 v[204:207], v158 offset:54272
	ds_read_b128 v[208:211], v158 offset:55296
	ds_read_b128 v[212:215], v158 offset:56320
	global_load_lds_dwordx4 v[216:217], off
	s_add_i32 m0, s19, 0x2000
	s_add_u32 s20, s86, 0x80080
	v_lshl_add_u64 v[216:217], v[218:219], 0, s[4:5]
	s_addc_u32 s21, s87, 0
	s_add_i32 s19, s22, s35
	global_load_lds_dwordx4 v[216:217], off
	v_lshl_add_u64 v[216:217], s[20:21], 0, v[134:135]
	s_mov_b32 m0, s19
	s_nop 0
	global_load_lds_dwordx4 v[216:217], off
	v_lshl_add_u64 v[216:217], s[20:21], 0, v[130:131]
	s_add_i32 m0, s19, 0x2000
	s_nop 0
	global_load_lds_dwordx4 v[216:217], off
	v_lshl_add_u64 v[216:217], v[220:221], 0, s[4:5]
	s_mov_b32 m0, s67
	s_nop 0
	global_load_lds_dwordx4 v[216:217], off
	v_lshl_add_u64 v[216:217], v[222:223], 0, s[4:5]
	s_mov_b32 m0, s68
	s_nop 0
	global_load_lds_dwordx4 v[216:217], off
	s_waitcnt vmcnt(8)
	s_waitcnt lgkmcnt(0)
	s_barrier
	v_mfma_i32_16x16x64_i8 v[62:65], v[146:149], v[184:187], v[62:65]
	v_mfma_i32_16x16x64_i8 v[58:61], v[160:163], v[184:187], v[58:61]
	v_mfma_i32_16x16x64_i8 v[46:49], v[146:149], v[192:195], v[46:49]
	v_mfma_i32_16x16x64_i8 v[42:45], v[160:163], v[192:195], v[42:45]
	v_mfma_i32_16x16x64_i8 v[30:33], v[146:149], v[200:203], v[30:33]
	v_mfma_i32_16x16x64_i8 v[26:29], v[160:163], v[200:203], v[26:29]
	v_mfma_i32_16x16x64_i8 v[14:17], v[146:149], v[208:211], v[14:17]
	v_mfma_i32_16x16x64_i8 v[10:13], v[160:163], v[208:211], v[10:13]
	v_mfma_i32_16x16x64_i8 v[62:65], v[150:153], v[188:191], v[62:65]
	v_mfma_i32_16x16x64_i8 v[58:61], v[164:167], v[188:191], v[58:61]
	v_mfma_i32_16x16x64_i8 v[46:49], v[150:153], v[196:199], v[46:49]
	v_mfma_i32_16x16x64_i8 v[42:45], v[164:167], v[196:199], v[42:45]
	v_mfma_i32_16x16x64_i8 v[30:33], v[150:153], v[204:207], v[30:33]
	v_mfma_i32_16x16x64_i8 v[26:29], v[164:167], v[204:207], v[26:29]
	v_mfma_i32_16x16x64_i8 v[14:17], v[150:153], v[212:215], v[14:17]
	v_mfma_i32_16x16x64_i8 v[10:13], v[164:167], v[212:215], v[10:13]
	v_mfma_i32_16x16x64_i8 v[54:57], v[168:171], v[184:187], v[54:57]
	v_mfma_i32_16x16x64_i8 v[50:53], v[176:179], v[184:187], v[50:53]
	v_mfma_i32_16x16x64_i8 v[38:41], v[168:171], v[192:195], v[38:41]
	v_mfma_i32_16x16x64_i8 v[34:37], v[176:179], v[192:195], v[34:37]
	v_mfma_i32_16x16x64_i8 v[22:25], v[168:171], v[200:203], v[22:25]
	v_mfma_i32_16x16x64_i8 v[18:21], v[176:179], v[200:203], v[18:21]
	v_mfma_i32_16x16x64_i8 v[6:9], v[168:171], v[208:211], v[6:9]
	v_mfma_i32_16x16x64_i8 v[2:5], v[176:179], v[208:211], v[2:5]
	v_mfma_i32_16x16x64_i8 v[54:57], v[172:175], v[188:191], v[54:57]
	v_mfma_i32_16x16x64_i8 v[50:53], v[180:183], v[188:191], v[50:53]
	v_mfma_i32_16x16x64_i8 v[38:41], v[172:175], v[196:199], v[38:41]
	v_mfma_i32_16x16x64_i8 v[34:37], v[180:183], v[196:199], v[34:37]
	v_mfma_i32_16x16x64_i8 v[22:25], v[172:175], v[204:207], v[22:25]
	v_mfma_i32_16x16x64_i8 v[18:21], v[180:183], v[204:207], v[18:21]
	v_mfma_i32_16x16x64_i8 v[6:9], v[172:175], v[212:215], v[6:9]
	v_mfma_i32_16x16x64_i8 v[2:5], v[180:183], v[212:215], v[2:5]
	s_barrier
	s_add_i32 s18, s18, 2
	s_add_u32 s84, s84, 0x100
	s_addc_u32 s85, s85, 0
	s_add_u32 s16, s16, 0x100
	s_addc_u32 s17, s17, 0
	s_cmp_gt_u32 s18, 29
	s_cbranch_scc0 .LBB0_213
	s_setprio 0
	s_and_b64 vcc, exec, s[6:7]
	s_cbranch_vccz .LBB0_216
	s_barrier

.Lsp_p3:
.LBB0_362:
	ds_read_b128 v[106:109], v168
	ds_read_b128 v[110:113], v168 offset:1024
	ds_read_b128 v[114:117], v168 offset:2048
	ds_read_b128 v[122:125], v168 offset:3072
	ds_read_b128 v[160:163], v169
	ds_read_b128 v[172:175], v169 offset:1024
	ds_read_b128 v[176:179], v169 offset:2048
	ds_read_b128 v[180:183], v169 offset:3072
	s_add_u32 s16, s6, 0xffea8080
	s_addc_u32 s17, s7, -1
	s_cmpk_eq_i32 s13, 0x52
	s_cselect_b32 s85, s51, s17
	s_cselect_b32 s84, s50, s16
	s_cselect_b32 s83, s81, s12
	s_cselect_b32 s82, s80, s8
	v_lshl_add_u64 v[216:217], s[6:7], 0, v[154:155]
	s_add_i32 m0, s56, 0xc000
	ds_read_b128 v[184:187], v170
	ds_read_b128 v[188:191], v170 offset:1024
	ds_read_b128 v[192:195], v170 offset:2048
	ds_read_b128 v[196:199], v170 offset:3072
	ds_read_b128 v[200:203], v170 offset:4096
	ds_read_b128 v[204:207], v170 offset:5120
	ds_read_b128 v[208:211], v170 offset:6144
	ds_read_b128 v[212:215], v170 offset:7168
	global_load_lds_dwordx4 v[216:217], off
	v_lshl_add_u64 v[216:217], s[6:7], 0, v[156:157]
	s_add_i32 m0, s56, 0xe000
	s_nop 0
	global_load_lds_dwordx4 v[216:217], off
	s_waitcnt vmcnt(8)
	s_waitcnt lgkmcnt(0)
	s_barrier
	v_mfma_i32_16x16x64_i8 v[142:145], v[106:109], v[184:187], v[142:145]
	v_mfma_i32_16x16x64_i8 v[138:141], v[114:117], v[184:187], v[138:141]
	v_mfma_i32_16x16x64_i8 v[126:129], v[106:109], v[192:195], v[126:129]
	v_mfma_i32_16x16x64_i8 v[118:121], v[114:117], v[192:195], v[118:121]
	v_mfma_i32_16x16x64_i8 v[94:97], v[106:109], v[200:203], v[94:97]
	v_mfma_i32_16x16x64_i8 v[90:93], v[114:117], v[200:203], v[90:93]
	v_mfma_i32_16x16x64_i8 v[78:81], v[106:109], v[208:211], v[78:81]
	v_mfma_i32_16x16x64_i8 v[74:77], v[114:117], v[208:211], v[74:77]
	v_mfma_i32_16x16x64_i8 v[142:145], v[110:113], v[188:191], v[142:145]
	v_mfma_i32_16x16x64_i8 v[138:141], v[122:125], v[188:191], v[138:141]
	v_mfma_i32_16x16x64_i8 v[126:129], v[110:113], v[196:199], v[126:129]
	v_mfma_i32_16x16x64_i8 v[118:121], v[122:125], v[196:199], v[118:121]
	v_mfma_i32_16x16x64_i8 v[94:97], v[110:113], v[204:207], v[94:97]
	v_mfma_i32_16x16x64_i8 v[90:93], v[122:125], v[204:207], v[90:93]
	v_mfma_i32_16x16x64_i8 v[78:81], v[110:113], v[212:215], v[78:81]
	v_mfma_i32_16x16x64_i8 v[74:77], v[122:125], v[212:215], v[74:77]
	v_mfma_i32_16x16x64_i8 v[134:137], v[160:163], v[184:187], v[134:137]
	v_mfma_i32_16x16x64_i8 v[130:133], v[176:179], v[184:187], v[130:133]
	v_mfma_i32_16x16x64_i8 v[102:105], v[160:163], v[192:195], v[102:105]
	v_mfma_i32_16x16x64_i8 v[98:101], v[176:179], v[192:195], v[98:101]
	v_mfma_i32_16x16x64_i8 v[86:89], v[160:163], v[200:203], v[86:89]
	v_mfma_i32_16x16x64_i8 v[82:85], v[176:179], v[200:203], v[82:85]
	v_mfma_i32_16x16x64_i8 v[70:73], v[160:163], v[208:211], v[70:73]
	v_mfma_i32_16x16x64_i8 v[66:69], v[176:179], v[208:211], v[66:69]
	v_mfma_i32_16x16x64_i8 v[134:137], v[172:175], v[188:191], v[134:137]
	v_mfma_i32_16x16x64_i8 v[130:133], v[180:183], v[188:191], v[130:133]
	v_mfma_i32_16x16x64_i8 v[102:105], v[172:175], v[196:199], v[102:105]
	v_mfma_i32_16x16x64_i8 v[98:101], v[180:183], v[196:199], v[98:101]
	v_mfma_i32_16x16x64_i8 v[86:89], v[172:175], v[204:207], v[86:89]
	v_mfma_i32_16x16x64_i8 v[82:85], v[180:183], v[204:207], v[82:85]
	v_mfma_i32_16x16x64_i8 v[70:73], v[172:175], v[212:215], v[70:73]
	v_mfma_i32_16x16x64_i8 v[66:69], v[180:183], v[212:215], v[66:69]
	s_barrier
	s_add_i32 s16, s87, s35
	v_lshl_add_u64 v[216:217], s[82:83], 0, v[148:149]
	s_mov_b32 m0, s16
	ds_read_b128 v[184:187], v170 offset:16384
	ds_read_b128 v[188:191], v170 offset:17408
	ds_read_b128 v[192:195], v170 offset:18432
	ds_read_b128 v[196:199], v170 offset:19456
	ds_read_b128 v[200:203], v170 offset:20480
	ds_read_b128 v[204:207], v170 offset:21504
	ds_read_b128 v[208:211], v170 offset:22528
	ds_read_b128 v[212:215], v170 offset:23552
	global_load_lds_dwordx4 v[216:217], off
	s_add_i32 m0, s16, 0x2000
	s_add_u32 s16, s82, 0x158000
	v_lshl_add_u64 v[218:219], s[82:83], 0, v[152:153]
	s_addc_u32 s17, s83, 0
	s_add_i32 s18, s88, s35
	global_load_lds_dwordx4 v[218:219], off
	v_lshl_add_u64 v[220:221], s[16:17], 0, v[148:149]
	s_mov_b32 m0, s18
	v_lshl_add_u64 v[222:223], s[84:85], 0, v[150:151]
	global_load_lds_dwordx4 v[220:221], off
	v_lshl_add_u64 v[220:221], s[16:17], 0, v[152:153]
	s_add_i32 m0, s18, 0x2000
	s_nop 0
	global_load_lds_dwordx4 v[220:221], off
	v_lshl_add_u64 v[220:221], s[84:85], 0, v[146:147]
	s_mov_b32 m0, s56
	s_nop 0
	global_load_lds_dwordx4 v[220:221], off
	s_mov_b32 m0, s57
	s_nop 0
	global_load_lds_dwordx4 v[222:223], off
	s_waitcnt vmcnt(8)
	s_waitcnt lgkmcnt(0)
	s_barrier
	v_mfma_i32_16x16x64_i8 v[62:65], v[106:109], v[184:187], v[62:65]
	v_mfma_i32_16x16x64_i8 v[58:61], v[114:117], v[184:187], v[58:61]
	v_mfma_i32_16x16x64_i8 v[46:49], v[106:109], v[192:195], v[46:49]
	v_mfma_i32_16x16x64_i8 v[42:45], v[114:117], v[192:195], v[42:45]
	v_mfma_i32_16x16x64_i8 v[30:33], v[106:109], v[200:203], v[30:33]
	v_mfma_i32_16x16x64_i8 v[26:29], v[114:117], v[200:203], v[26:29]
	v_mfma_i32_16x16x64_i8 v[14:17], v[106:109], v[208:211], v[14:17]
	v_mfma_i32_16x16x64_i8 v[10:13], v[114:117], v[208:211], v[10:13]
	v_mfma_i32_16x16x64_i8 v[62:65], v[110:113], v[188:191], v[62:65]
	v_mfma_i32_16x16x64_i8 v[58:61], v[122:125], v[188:191], v[58:61]
	v_mfma_i32_16x16x64_i8 v[46:49], v[110:113], v[196:199], v[46:49]
	v_mfma_i32_16x16x64_i8 v[42:45], v[122:125], v[196:199], v[42:45]
	v_mfma_i32_16x16x64_i8 v[30:33], v[110:113], v[204:207], v[30:33]
	v_mfma_i32_16x16x64_i8 v[26:29], v[122:125], v[204:207], v[26:29]
	v_mfma_i32_16x16x64_i8 v[14:17], v[110:113], v[212:215], v[14:17]
	v_mfma_i32_16x16x64_i8 v[10:13], v[122:125], v[212:215], v[10:13]
	v_mfma_i32_16x16x64_i8 v[54:57], v[160:163], v[184:187], v[54:57]
	v_mfma_i32_16x16x64_i8 v[50:53], v[176:179], v[184:187], v[50:53]
	v_mfma_i32_16x16x64_i8 v[38:41], v[160:163], v[192:195], v[38:41]
	v_mfma_i32_16x16x64_i8 v[34:37], v[176:179], v[192:195], v[34:37]
	v_mfma_i32_16x16x64_i8 v[22:25], v[160:163], v[200:203], v[22:25]
	v_mfma_i32_16x16x64_i8 v[18:21], v[176:179], v[200:203], v[18:21]
	v_mfma_i32_16x16x64_i8 v[6:9], v[160:163], v[208:211], v[6:9]
	v_mfma_i32_16x16x64_i8 v[2:5], v[176:179], v[208:211], v[2:5]
	v_mfma_i32_16x16x64_i8 v[54:57], v[172:175], v[188:191], v[54:57]
	v_mfma_i32_16x16x64_i8 v[50:53], v[180:183], v[188:191], v[50:53]
	v_mfma_i32_16x16x64_i8 v[38:41], v[172:175], v[196:199], v[38:41]
	v_mfma_i32_16x16x64_i8 v[34:37], v[180:183], v[196:199], v[34:37]
	v_mfma_i32_16x16x64_i8 v[22:25], v[172:175], v[204:207], v[22:25]
	v_mfma_i32_16x16x64_i8 v[18:21], v[180:183], v[204:207], v[18:21]
	v_mfma_i32_16x16x64_i8 v[6:9], v[172:175], v[212:215], v[6:9]
	v_mfma_i32_16x16x64_i8 v[2:5], v[180:183], v[212:215], v[2:5]
	s_barrier
	s_add_i32 s18, 0, 0x18000
	s_add_i32 s19, 0, 0x1c000
	v_add_u32_e32 v122, s18, v165
	v_add_u32_e32 v164, s19, v165
	ds_read_b128 v[106:109], v122
	ds_read_b128 v[110:113], v122 offset:1024
	ds_read_b128 v[114:117], v122 offset:2048
	ds_read_b128 v[122:125], v122 offset:3072
	ds_read_b128 v[160:163], v164
	ds_read_b128 v[172:175], v164 offset:1024
	ds_read_b128 v[176:179], v164 offset:2048
	ds_read_b128 v[180:183], v164 offset:3072
	s_add_u32 s16, s84, 0x158000
	s_addc_u32 s17, s85, 0
	s_mov_b32 m0, s58
	v_lshl_add_u64 v[224:225], s[16:17], 0, v[146:147]
	ds_read_b128 v[184:187], v170 offset:32768
	ds_read_b128 v[188:191], v170 offset:33792
	ds_read_b128 v[192:195], v170 offset:34816
	ds_read_b128 v[196:199], v170 offset:35840
	ds_read_b128 v[200:203], v170 offset:36864
	ds_read_b128 v[204:207], v170 offset:37888
	ds_read_b128 v[208:211], v170 offset:38912
	ds_read_b128 v[212:215], v170 offset:39936
	global_load_lds_dwordx4 v[224:225], off
	v_lshl_add_u64 v[224:225], s[16:17], 0, v[150:151]
	s_mov_b32 m0, s59
	s_nop 0
	global_load_lds_dwordx4 v[224:225], off
	s_waitcnt vmcnt(8)
	s_waitcnt lgkmcnt(0)
	s_barrier
	v_mfma_i32_16x16x64_i8 v[142:145], v[106:109], v[184:187], v[142:145]
	v_mfma_i32_16x16x64_i8 v[138:141], v[114:117], v[184:187], v[138:141]
	v_mfma_i32_16x16x64_i8 v[126:129], v[106:109], v[192:195], v[126:129]
	v_mfma_i32_16x16x64_i8 v[118:121], v[114:117], v[192:195], v[118:121]
	v_mfma_i32_16x16x64_i8 v[94:97], v[106:109], v[200:203], v[94:97]
	v_mfma_i32_16x16x64_i8 v[90:93], v[114:117], v[200:203], v[90:93]
	v_mfma_i32_16x16x64_i8 v[78:81], v[106:109], v[208:211], v[78:81]
	v_mfma_i32_16x16x64_i8 v[74:77], v[114:117], v[208:211], v[74:77]
	v_mfma_i32_16x16x64_i8 v[142:145], v[110:113], v[188:191], v[142:145]
	v_mfma_i32_16x16x64_i8 v[138:141], v[122:125], v[188:191], v[138:141]
	v_mfma_i32_16x16x64_i8 v[126:129], v[110:113], v[196:199], v[126:129]
	v_mfma_i32_16x16x64_i8 v[118:121], v[122:125], v[196:199], v[118:121]
	v_mfma_i32_16x16x64_i8 v[94:97], v[110:113], v[204:207], v[94:97]
	v_mfma_i32_16x16x64_i8 v[90:93], v[122:125], v[204:207], v[90:93]
	v_mfma_i32_16x16x64_i8 v[78:81], v[110:113], v[212:215], v[78:81]
	v_mfma_i32_16x16x64_i8 v[74:77], v[122:125], v[212:215], v[74:77]
	v_mfma_i32_16x16x64_i8 v[134:137], v[160:163], v[184:187], v[134:137]
	v_mfma_i32_16x16x64_i8 v[130:133], v[176:179], v[184:187], v[130:133]
	v_mfma_i32_16x16x64_i8 v[102:105], v[160:163], v[192:195], v[102:105]
	v_mfma_i32_16x16x64_i8 v[98:101], v[176:179], v[192:195], v[98:101]
	v_mfma_i32_16x16x64_i8 v[86:89], v[160:163], v[200:203], v[86:89]
	v_mfma_i32_16x16x64_i8 v[82:85], v[176:179], v[200:203], v[82:85]
	v_mfma_i32_16x16x64_i8 v[70:73], v[160:163], v[208:211], v[70:73]
	v_mfma_i32_16x16x64_i8 v[66:69], v[176:179], v[208:211], v[66:69]
	v_mfma_i32_16x16x64_i8 v[134:137], v[172:175], v[188:191], v[134:137]
	v_mfma_i32_16x16x64_i8 v[130:133], v[180:183], v[188:191], v[130:133]
	v_mfma_i32_16x16x64_i8 v[102:105], v[172:175], v[196:199], v[102:105]
	v_mfma_i32_16x16x64_i8 v[98:101], v[180:183], v[196:199], v[98:101]
	v_mfma_i32_16x16x64_i8 v[86:89], v[172:175], v[204:207], v[86:89]
	v_mfma_i32_16x16x64_i8 v[82:85], v[180:183], v[204:207], v[82:85]
	v_mfma_i32_16x16x64_i8 v[70:73], v[172:175], v[212:215], v[70:73]
	v_mfma_i32_16x16x64_i8 v[66:69], v[180:183], v[212:215], v[66:69]
	s_barrier
	s_add_i32 s16, s18, s35
	v_lshl_add_u64 v[216:217], v[216:217], 0, s[44:45]
	s_mov_b32 m0, s16
	ds_read_b128 v[184:187], v170 offset:49152
	ds_read_b128 v[188:191], v170 offset:50176
	ds_read_b128 v[192:195], v170 offset:51200
	ds_read_b128 v[196:199], v170 offset:52224
	ds_read_b128 v[200:203], v170 offset:53248
	ds_read_b128 v[204:207], v170 offset:54272
	ds_read_b128 v[208:211], v170 offset:55296
	ds_read_b128 v[212:215], v170 offset:56320
	global_load_lds_dwordx4 v[216:217], off
	s_add_i32 m0, s16, 0x2000
	s_add_u32 s16, s82, 0x158080
	v_lshl_add_u64 v[216:217], v[218:219], 0, s[44:45]
	s_addc_u32 s17, s83, 0
	s_add_i32 s18, s19, s35
	global_load_lds_dwordx4 v[216:217], off
	v_lshl_add_u64 v[216:217], s[16:17], 0, v[148:149]
	s_mov_b32 m0, s18
	s_nop 0
	global_load_lds_dwordx4 v[216:217], off
	v_lshl_add_u64 v[216:217], s[16:17], 0, v[152:153]
	s_add_i32 m0, s18, 0x2000
	s_nop 0
	global_load_lds_dwordx4 v[216:217], off
	v_lshl_add_u64 v[216:217], v[220:221], 0, s[44:45]
	s_mov_b32 m0, s61
	s_nop 0
	global_load_lds_dwordx4 v[216:217], off
	v_lshl_add_u64 v[216:217], v[222:223], 0, s[44:45]
	s_mov_b32 m0, s66
	s_nop 0
	global_load_lds_dwordx4 v[216:217], off
	s_waitcnt vmcnt(8)
	s_waitcnt lgkmcnt(0)
	s_barrier
	v_mfma_i32_16x16x64_i8 v[62:65], v[106:109], v[184:187], v[62:65]
	v_mfma_i32_16x16x64_i8 v[58:61], v[114:117], v[184:187], v[58:61]
	v_mfma_i32_16x16x64_i8 v[46:49], v[106:109], v[192:195], v[46:49]
	v_mfma_i32_16x16x64_i8 v[42:45], v[114:117], v[192:195], v[42:45]
	v_mfma_i32_16x16x64_i8 v[30:33], v[106:109], v[200:203], v[30:33]
	v_mfma_i32_16x16x64_i8 v[26:29], v[114:117], v[200:203], v[26:29]
	v_mfma_i32_16x16x64_i8 v[14:17], v[106:109], v[208:211], v[14:17]
	v_mfma_i32_16x16x64_i8 v[10:13], v[114:117], v[208:211], v[10:13]
	v_mfma_i32_16x16x64_i8 v[62:65], v[110:113], v[188:191], v[62:65]
	v_mfma_i32_16x16x64_i8 v[58:61], v[122:125], v[188:191], v[58:61]
	v_mfma_i32_16x16x64_i8 v[46:49], v[110:113], v[196:199], v[46:49]
	v_mfma_i32_16x16x64_i8 v[42:45], v[122:125], v[196:199], v[42:45]
	v_mfma_i32_16x16x64_i8 v[30:33], v[110:113], v[204:207], v[30:33]
	v_mfma_i32_16x16x64_i8 v[26:29], v[122:125], v[204:207], v[26:29]
	v_mfma_i32_16x16x64_i8 v[14:17], v[110:113], v[212:215], v[14:17]
	v_mfma_i32_16x16x64_i8 v[10:13], v[122:125], v[212:215], v[10:13]
	v_mfma_i32_16x16x64_i8 v[54:57], v[160:163], v[184:187], v[54:57]
	v_mfma_i32_16x16x64_i8 v[50:53], v[176:179], v[184:187], v[50:53]
	v_mfma_i32_16x16x64_i8 v[38:41], v[160:163], v[192:195], v[38:41]
	v_mfma_i32_16x16x64_i8 v[34:37], v[176:179], v[192:195], v[34:37]
	v_mfma_i32_16x16x64_i8 v[22:25], v[160:163], v[200:203], v[22:25]
	v_mfma_i32_16x16x64_i8 v[18:21], v[176:179], v[200:203], v[18:21]
	v_mfma_i32_16x16x64_i8 v[6:9], v[160:163], v[208:211], v[6:9]
	v_mfma_i32_16x16x64_i8 v[2:5], v[176:179], v[208:211], v[2:5]
	v_mfma_i32_16x16x64_i8 v[54:57], v[172:175], v[188:191], v[54:57]
	v_mfma_i32_16x16x64_i8 v[50:53], v[180:183], v[188:191], v[50:53]
	v_mfma_i32_16x16x64_i8 v[38:41], v[172:175], v[196:199], v[38:41]
	v_mfma_i32_16x16x64_i8 v[34:37], v[180:183], v[196:199], v[34:37]
	v_mfma_i32_16x16x64_i8 v[22:25], v[172:175], v[204:207], v[22:25]
	v_mfma_i32_16x16x64_i8 v[18:21], v[180:183], v[204:207], v[18:21]
	v_mfma_i32_16x16x64_i8 v[6:9], v[172:175], v[212:215], v[6:9]
	v_mfma_i32_16x16x64_i8 v[2:5], v[180:183], v[212:215], v[2:5]
	s_barrier
	s_add_i32 s13, s13, 2
	s_add_u32 s6, s6, 0x100
	s_addc_u32 s7, s7, 0
	s_add_u32 s8, s8, 0x100
	s_addc_u32 s12, s12, 0
	s_cmpk_gt_u32 s13, 0x53
	s_cbranch_scc0 .LBB0_362
	s_setprio 0
	s_and_b64 vcc, exec, s[46:47]
	s_cbranch_vccz .LBB0_365
	s_barrier

.Lsp_p5:
.LBB0_541:
	ds_read_b128 v[146:149], v154
	ds_read_b128 v[158:161], v154 offset:1024
	ds_read_b128 v[162:165], v154 offset:2048
	ds_read_b128 v[166:169], v154 offset:3072
	ds_read_b128 v[170:173], v155
	ds_read_b128 v[174:177], v155 offset:1024
	ds_read_b128 v[178:181], v155 offset:2048
	ds_read_b128 v[182:185], v155 offset:3072
	s_add_u32 s18, s84, 0xfff00080
	s_addc_u32 s19, s85, -1
	s_cmp_eq_u32 s17, 60
	s_cselect_b32 s89, s5, s19
	s_cselect_b32 s88, s8, s18
	s_cselect_b32 s87, s9, s16
	s_cselect_b32 s86, s12, s13
	v_lshl_add_u64 v[218:219], s[84:85], 0, v[138:139]
	s_add_i32 m0, s56, 0xc000
	ds_read_b128 v[186:189], v156
	ds_read_b128 v[190:193], v156 offset:1024
	ds_read_b128 v[194:197], v156 offset:2048
	ds_read_b128 v[198:201], v156 offset:3072
	ds_read_b128 v[202:205], v156 offset:4096
	ds_read_b128 v[206:209], v156 offset:5120
	ds_read_b128 v[210:213], v156 offset:6144
	ds_read_b128 v[214:217], v156 offset:7168
	global_load_lds_dwordx4 v[218:219], off
	v_lshl_add_u64 v[218:219], s[84:85], 0, v[140:141]
	s_add_i32 m0, s56, 0xe000
	s_nop 0
	global_load_lds_dwordx4 v[218:219], off
	s_waitcnt vmcnt(8)
	s_waitcnt lgkmcnt(0)
	s_barrier
	v_mfma_f32_16x16x32_bf16 v[126:129], v[146:149], v[186:189], v[126:129]
	v_mfma_f32_16x16x32_bf16 v[122:125], v[162:165], v[186:189], v[122:125]
	v_mfma_f32_16x16x32_bf16 v[110:113], v[146:149], v[194:197], v[110:113]
	v_mfma_f32_16x16x32_bf16 v[106:109], v[162:165], v[194:197], v[106:109]
	v_mfma_f32_16x16x32_bf16 v[94:97], v[146:149], v[202:205], v[94:97]
	v_mfma_f32_16x16x32_bf16 v[90:93], v[162:165], v[202:205], v[90:93]
	v_mfma_f32_16x16x32_bf16 v[78:81], v[146:149], v[210:213], v[78:81]
	v_mfma_f32_16x16x32_bf16 v[74:77], v[162:165], v[210:213], v[74:77]
	v_mfma_f32_16x16x32_bf16 v[126:129], v[158:161], v[190:193], v[126:129]
	v_mfma_f32_16x16x32_bf16 v[122:125], v[166:169], v[190:193], v[122:125]
	v_mfma_f32_16x16x32_bf16 v[110:113], v[158:161], v[198:201], v[110:113]
	v_mfma_f32_16x16x32_bf16 v[106:109], v[166:169], v[198:201], v[106:109]
	v_mfma_f32_16x16x32_bf16 v[94:97], v[158:161], v[206:209], v[94:97]
	v_mfma_f32_16x16x32_bf16 v[90:93], v[166:169], v[206:209], v[90:93]
	v_mfma_f32_16x16x32_bf16 v[78:81], v[158:161], v[214:217], v[78:81]
	v_mfma_f32_16x16x32_bf16 v[74:77], v[166:169], v[214:217], v[74:77]
	v_mfma_f32_16x16x32_bf16 v[118:121], v[170:173], v[186:189], v[118:121]
	v_mfma_f32_16x16x32_bf16 v[114:117], v[178:181], v[186:189], v[114:117]
	v_mfma_f32_16x16x32_bf16 v[102:105], v[170:173], v[194:197], v[102:105]
	v_mfma_f32_16x16x32_bf16 v[98:101], v[178:181], v[194:197], v[98:101]
	v_mfma_f32_16x16x32_bf16 v[86:89], v[170:173], v[202:205], v[86:89]
	v_mfma_f32_16x16x32_bf16 v[82:85], v[178:181], v[202:205], v[82:85]
	v_mfma_f32_16x16x32_bf16 v[70:73], v[170:173], v[210:213], v[70:73]
	v_mfma_f32_16x16x32_bf16 v[66:69], v[178:181], v[210:213], v[66:69]
	v_mfma_f32_16x16x32_bf16 v[118:121], v[174:177], v[190:193], v[118:121]
	v_mfma_f32_16x16x32_bf16 v[114:117], v[182:185], v[190:193], v[114:117]
	v_mfma_f32_16x16x32_bf16 v[102:105], v[174:177], v[198:201], v[102:105]
	v_mfma_f32_16x16x32_bf16 v[98:101], v[182:185], v[198:201], v[98:101]
	v_mfma_f32_16x16x32_bf16 v[86:89], v[174:177], v[206:209], v[86:89]
	v_mfma_f32_16x16x32_bf16 v[82:85], v[182:185], v[206:209], v[82:85]
	v_mfma_f32_16x16x32_bf16 v[70:73], v[174:177], v[214:217], v[70:73]
	v_mfma_f32_16x16x32_bf16 v[66:69], v[182:185], v[214:217], v[66:69]
	s_barrier
	s_add_i32 s18, s83, s35
	v_lshl_add_u64 v[218:219], s[86:87], 0, v[132:133]
	s_mov_b32 m0, s18
	ds_read_b128 v[186:189], v156 offset:16384
	ds_read_b128 v[190:193], v156 offset:17408
	ds_read_b128 v[194:197], v156 offset:18432
	ds_read_b128 v[198:201], v156 offset:19456
	ds_read_b128 v[202:205], v156 offset:20480
	ds_read_b128 v[206:209], v156 offset:21504
	ds_read_b128 v[210:213], v156 offset:22528
	ds_read_b128 v[214:217], v156 offset:23552
	global_load_lds_dwordx4 v[218:219], off
	s_add_i32 m0, s18, 0x2000
	s_add_u32 s18, s86, 0x100000
	v_lshl_add_u64 v[220:221], s[86:87], 0, v[136:137]
	s_addc_u32 s19, s87, 0
	s_add_i32 s20, s90, s35
	global_load_lds_dwordx4 v[220:221], off
	v_lshl_add_u64 v[222:223], s[18:19], 0, v[132:133]
	s_mov_b32 m0, s20
	v_lshl_add_u64 v[224:225], s[88:89], 0, v[134:135]
	global_load_lds_dwordx4 v[222:223], off
	v_lshl_add_u64 v[222:223], s[18:19], 0, v[136:137]
	s_add_i32 m0, s20, 0x2000
	s_nop 0
	global_load_lds_dwordx4 v[222:223], off
	v_lshl_add_u64 v[222:223], s[88:89], 0, v[130:131]
	s_mov_b32 m0, s56
	s_nop 0
	global_load_lds_dwordx4 v[222:223], off
	s_mov_b32 m0, s57
	s_nop 0
	global_load_lds_dwordx4 v[224:225], off
	s_waitcnt vmcnt(8)
	s_waitcnt lgkmcnt(0)
	s_barrier
	v_mfma_f32_16x16x32_bf16 v[62:65], v[146:149], v[186:189], v[62:65]
	v_mfma_f32_16x16x32_bf16 v[58:61], v[162:165], v[186:189], v[58:61]
	v_mfma_f32_16x16x32_bf16 v[46:49], v[146:149], v[194:197], v[46:49]
	v_mfma_f32_16x16x32_bf16 v[42:45], v[162:165], v[194:197], v[42:45]
	v_mfma_f32_16x16x32_bf16 v[30:33], v[146:149], v[202:205], v[30:33]
	v_mfma_f32_16x16x32_bf16 v[26:29], v[162:165], v[202:205], v[26:29]
	v_mfma_f32_16x16x32_bf16 v[14:17], v[146:149], v[210:213], v[14:17]
	v_mfma_f32_16x16x32_bf16 v[10:13], v[162:165], v[210:213], v[10:13]
	v_mfma_f32_16x16x32_bf16 v[62:65], v[158:161], v[190:193], v[62:65]
	v_mfma_f32_16x16x32_bf16 v[58:61], v[166:169], v[190:193], v[58:61]
	v_mfma_f32_16x16x32_bf16 v[46:49], v[158:161], v[198:201], v[46:49]
	v_mfma_f32_16x16x32_bf16 v[42:45], v[166:169], v[198:201], v[42:45]
	v_mfma_f32_16x16x32_bf16 v[30:33], v[158:161], v[206:209], v[30:33]
	v_mfma_f32_16x16x32_bf16 v[26:29], v[166:169], v[206:209], v[26:29]
	v_mfma_f32_16x16x32_bf16 v[14:17], v[158:161], v[214:217], v[14:17]
	v_mfma_f32_16x16x32_bf16 v[10:13], v[166:169], v[214:217], v[10:13]
	v_mfma_f32_16x16x32_bf16 v[54:57], v[170:173], v[186:189], v[54:57]
	v_mfma_f32_16x16x32_bf16 v[50:53], v[178:181], v[186:189], v[50:53]
	v_mfma_f32_16x16x32_bf16 v[38:41], v[170:173], v[194:197], v[38:41]
	v_mfma_f32_16x16x32_bf16 v[34:37], v[178:181], v[194:197], v[34:37]
	v_mfma_f32_16x16x32_bf16 v[22:25], v[170:173], v[202:205], v[22:25]
	v_mfma_f32_16x16x32_bf16 v[18:21], v[178:181], v[202:205], v[18:21]
	v_mfma_f32_16x16x32_bf16 v[6:9], v[170:173], v[210:213], v[6:9]
	v_mfma_f32_16x16x32_bf16 v[2:5], v[178:181], v[210:213], v[2:5]
	v_mfma_f32_16x16x32_bf16 v[54:57], v[174:177], v[190:193], v[54:57]
	v_mfma_f32_16x16x32_bf16 v[50:53], v[182:185], v[190:193], v[50:53]
	v_mfma_f32_16x16x32_bf16 v[38:41], v[174:177], v[198:201], v[38:41]
	v_mfma_f32_16x16x32_bf16 v[34:37], v[182:185], v[198:201], v[34:37]
	v_mfma_f32_16x16x32_bf16 v[22:25], v[174:177], v[206:209], v[22:25]
	v_mfma_f32_16x16x32_bf16 v[18:21], v[182:185], v[206:209], v[18:21]
	v_mfma_f32_16x16x32_bf16 v[6:9], v[174:177], v[214:217], v[6:9]
	v_mfma_f32_16x16x32_bf16 v[2:5], v[182:185], v[214:217], v[2:5]
	s_barrier
	s_add_i32 s20, 0, 0x18000
	v_add_u32_e32 v150, s20, v151
	s_add_i32 s21, 0, 0x1c000
	ds_read_b128 v[146:149], v150
	ds_read_b128 v[158:161], v150 offset:1024
	ds_read_b128 v[162:165], v150 offset:2048
	ds_read_b128 v[166:169], v150 offset:3072
	v_add_u32_e32 v150, s21, v151
	ds_read_b128 v[170:173], v150
	ds_read_b128 v[174:177], v150 offset:1024
	ds_read_b128 v[178:181], v150 offset:2048
	ds_read_b128 v[182:185], v150 offset:3072
	s_add_u32 s18, s88, 0x100000
	s_addc_u32 s19, s89, 0
	s_mov_b32 m0, s58
	v_lshl_add_u64 v[228:229], s[18:19], 0, v[130:131]
	ds_read_b128 v[186:189], v156 offset:32768
	ds_read_b128 v[190:193], v156 offset:33792
	ds_read_b128 v[194:197], v156 offset:34816
	ds_read_b128 v[198:201], v156 offset:35840
	ds_read_b128 v[202:205], v156 offset:36864
	ds_read_b128 v[206:209], v156 offset:37888
	ds_read_b128 v[210:213], v156 offset:38912
	ds_read_b128 v[214:217], v156 offset:39936
	global_load_lds_dwordx4 v[228:229], off
	v_lshl_add_u64 v[228:229], s[18:19], 0, v[134:135]
	s_mov_b32 m0, s59
	s_nop 0
	global_load_lds_dwordx4 v[228:229], off
	s_waitcnt vmcnt(8)
	s_waitcnt lgkmcnt(0)
	s_barrier
	v_mfma_f32_16x16x32_bf16 v[126:129], v[146:149], v[186:189], v[126:129]
	v_mfma_f32_16x16x32_bf16 v[122:125], v[162:165], v[186:189], v[122:125]
	v_mfma_f32_16x16x32_bf16 v[110:113], v[146:149], v[194:197], v[110:113]
	v_mfma_f32_16x16x32_bf16 v[106:109], v[162:165], v[194:197], v[106:109]
	v_mfma_f32_16x16x32_bf16 v[94:97], v[146:149], v[202:205], v[94:97]
	v_mfma_f32_16x16x32_bf16 v[90:93], v[162:165], v[202:205], v[90:93]
	v_mfma_f32_16x16x32_bf16 v[78:81], v[146:149], v[210:213], v[78:81]
	v_mfma_f32_16x16x32_bf16 v[74:77], v[162:165], v[210:213], v[74:77]
	v_mfma_f32_16x16x32_bf16 v[126:129], v[158:161], v[190:193], v[126:129]
	v_mfma_f32_16x16x32_bf16 v[122:125], v[166:169], v[190:193], v[122:125]
	v_mfma_f32_16x16x32_bf16 v[110:113], v[158:161], v[198:201], v[110:113]
	v_mfma_f32_16x16x32_bf16 v[106:109], v[166:169], v[198:201], v[106:109]
	v_mfma_f32_16x16x32_bf16 v[94:97], v[158:161], v[206:209], v[94:97]
	v_mfma_f32_16x16x32_bf16 v[90:93], v[166:169], v[206:209], v[90:93]
	v_mfma_f32_16x16x32_bf16 v[78:81], v[158:161], v[214:217], v[78:81]
	v_mfma_f32_16x16x32_bf16 v[74:77], v[166:169], v[214:217], v[74:77]
	v_mfma_f32_16x16x32_bf16 v[118:121], v[170:173], v[186:189], v[118:121]
	v_mfma_f32_16x16x32_bf16 v[114:117], v[178:181], v[186:189], v[114:117]
	v_mfma_f32_16x16x32_bf16 v[102:105], v[170:173], v[194:197], v[102:105]
	v_mfma_f32_16x16x32_bf16 v[98:101], v[178:181], v[194:197], v[98:101]
	v_mfma_f32_16x16x32_bf16 v[86:89], v[170:173], v[202:205], v[86:89]
	v_mfma_f32_16x16x32_bf16 v[82:85], v[178:181], v[202:205], v[82:85]
	v_mfma_f32_16x16x32_bf16 v[70:73], v[170:173], v[210:213], v[70:73]
	v_mfma_f32_16x16x32_bf16 v[66:69], v[178:181], v[210:213], v[66:69]
	v_mfma_f32_16x16x32_bf16 v[118:121], v[174:177], v[190:193], v[118:121]
	v_mfma_f32_16x16x32_bf16 v[114:117], v[182:185], v[190:193], v[114:117]
	v_mfma_f32_16x16x32_bf16 v[102:105], v[174:177], v[198:201], v[102:105]
	v_mfma_f32_16x16x32_bf16 v[98:101], v[182:185], v[198:201], v[98:101]
	v_mfma_f32_16x16x32_bf16 v[86:89], v[174:177], v[206:209], v[86:89]
	v_mfma_f32_16x16x32_bf16 v[82:85], v[182:185], v[206:209], v[82:85]
	v_mfma_f32_16x16x32_bf16 v[70:73], v[174:177], v[214:217], v[70:73]
	v_mfma_f32_16x16x32_bf16 v[66:69], v[182:185], v[214:217], v[66:69]
	s_barrier
	s_add_i32 s18, s20, s35
	v_lshl_add_u64 v[218:219], v[218:219], 0, s[40:41]
	s_mov_b32 m0, s18
	ds_read_b128 v[186:189], v156 offset:49152
	ds_read_b128 v[190:193], v156 offset:50176
	ds_read_b128 v[194:197], v156 offset:51200
	ds_read_b128 v[198:201], v156 offset:52224
	ds_read_b128 v[202:205], v156 offset:53248
	ds_read_b128 v[206:209], v156 offset:54272
	ds_read_b128 v[210:213], v156 offset:55296
	ds_read_b128 v[214:217], v156 offset:56320
	global_load_lds_dwordx4 v[218:219], off
	s_add_i32 m0, s18, 0x2000
	s_add_u32 s18, s86, 0x100080
	v_lshl_add_u64 v[218:219], v[220:221], 0, s[40:41]
	s_addc_u32 s19, s87, 0
	s_add_i32 s20, s21, s35
	global_load_lds_dwordx4 v[218:219], off
	v_lshl_add_u64 v[218:219], s[18:19], 0, v[132:133]
	s_mov_b32 m0, s20
	s_nop 0
	global_load_lds_dwordx4 v[218:219], off
	v_lshl_add_u64 v[218:219], s[18:19], 0, v[136:137]
	s_add_i32 m0, s20, 0x2000
	s_nop 0
	global_load_lds_dwordx4 v[218:219], off
	v_lshl_add_u64 v[218:219], v[222:223], 0, s[40:41]
	s_mov_b32 m0, s66
	s_nop 0
	global_load_lds_dwordx4 v[218:219], off
	v_lshl_add_u64 v[218:219], v[224:225], 0, s[40:41]
	s_mov_b32 m0, s67
	s_nop 0
	global_load_lds_dwordx4 v[218:219], off
	s_waitcnt vmcnt(8)
	s_waitcnt lgkmcnt(0)
	s_barrier
	v_mfma_f32_16x16x32_bf16 v[62:65], v[146:149], v[186:189], v[62:65]
	v_mfma_f32_16x16x32_bf16 v[58:61], v[162:165], v[186:189], v[58:61]
	v_mfma_f32_16x16x32_bf16 v[46:49], v[146:149], v[194:197], v[46:49]
	v_mfma_f32_16x16x32_bf16 v[42:45], v[162:165], v[194:197], v[42:45]
	v_mfma_f32_16x16x32_bf16 v[30:33], v[146:149], v[202:205], v[30:33]
	v_mfma_f32_16x16x32_bf16 v[26:29], v[162:165], v[202:205], v[26:29]
	v_mfma_f32_16x16x32_bf16 v[14:17], v[146:149], v[210:213], v[14:17]
	v_mfma_f32_16x16x32_bf16 v[10:13], v[162:165], v[210:213], v[10:13]
	v_mfma_f32_16x16x32_bf16 v[62:65], v[158:161], v[190:193], v[62:65]
	v_mfma_f32_16x16x32_bf16 v[58:61], v[166:169], v[190:193], v[58:61]
	v_mfma_f32_16x16x32_bf16 v[46:49], v[158:161], v[198:201], v[46:49]
	v_mfma_f32_16x16x32_bf16 v[42:45], v[166:169], v[198:201], v[42:45]
	v_mfma_f32_16x16x32_bf16 v[30:33], v[158:161], v[206:209], v[30:33]
	v_mfma_f32_16x16x32_bf16 v[26:29], v[166:169], v[206:209], v[26:29]
	v_mfma_f32_16x16x32_bf16 v[14:17], v[158:161], v[214:217], v[14:17]
	v_mfma_f32_16x16x32_bf16 v[10:13], v[166:169], v[214:217], v[10:13]
	v_mfma_f32_16x16x32_bf16 v[54:57], v[170:173], v[186:189], v[54:57]
	v_mfma_f32_16x16x32_bf16 v[50:53], v[178:181], v[186:189], v[50:53]
	v_mfma_f32_16x16x32_bf16 v[38:41], v[170:173], v[194:197], v[38:41]
	v_mfma_f32_16x16x32_bf16 v[34:37], v[178:181], v[194:197], v[34:37]
	v_mfma_f32_16x16x32_bf16 v[22:25], v[170:173], v[202:205], v[22:25]
	v_mfma_f32_16x16x32_bf16 v[18:21], v[178:181], v[202:205], v[18:21]
	v_mfma_f32_16x16x32_bf16 v[6:9], v[170:173], v[210:213], v[6:9]
	v_mfma_f32_16x16x32_bf16 v[2:5], v[178:181], v[210:213], v[2:5]
	v_mfma_f32_16x16x32_bf16 v[54:57], v[174:177], v[190:193], v[54:57]
	v_mfma_f32_16x16x32_bf16 v[50:53], v[182:185], v[190:193], v[50:53]
	v_mfma_f32_16x16x32_bf16 v[38:41], v[174:177], v[198:201], v[38:41]
	v_mfma_f32_16x16x32_bf16 v[34:37], v[182:185], v[198:201], v[34:37]
	v_mfma_f32_16x16x32_bf16 v[22:25], v[174:177], v[206:209], v[22:25]
	v_mfma_f32_16x16x32_bf16 v[18:21], v[182:185], v[206:209], v[18:21]
	v_mfma_f32_16x16x32_bf16 v[6:9], v[174:177], v[214:217], v[6:9]
	v_mfma_f32_16x16x32_bf16 v[2:5], v[182:185], v[214:217], v[2:5]
	s_barrier
	s_add_i32 s17, s17, 2
	s_add_u32 s84, s84, 0x100
	s_addc_u32 s85, s85, 0
	s_add_u32 s13, s13, 0x100
	s_addc_u32 s16, s16, 0
	s_cmp_gt_u32 s17, 61
	s_cbranch_scc0 .LBB0_541
	s_setprio 0
	s_and_b64 vcc, exec, s[42:43]
	s_cbranch_vccz .LBB0_544
	s_barrier

.Lsp_p9:
.LBB0_886:
	ds_read_b128 v[154:157], v150
	ds_read_b128 v[158:161], v150 offset:1024
	ds_read_b128 v[162:165], v150 offset:2048
	ds_read_b128 v[166:169], v150 offset:3072
	ds_read_b128 v[170:173], v151
	ds_read_b128 v[174:177], v151 offset:1024
	ds_read_b128 v[178:181], v151 offset:2048
	ds_read_b128 v[182:185], v151 offset:3072
	s_add_u32 s50, s48, 0xfff00080
	s_addc_u32 s51, s49, -1
	s_cmp_eq_u32 s78, 60
	s_cselect_b32 s53, s8, s51
	s_cselect_b32 s52, s9, s50
	s_cselect_b32 s51, s12, s41
	s_cselect_b32 s50, s13, s29
	v_lshl_add_u64 v[146:147], s[48:49], 0, v[138:139]
	s_add_i32 m0, s47, 0xc000
	ds_read_b128 v[186:189], v152
	ds_read_b128 v[190:193], v152 offset:1024
	ds_read_b128 v[194:197], v152 offset:2048
	ds_read_b128 v[198:201], v152 offset:3072
	ds_read_b128 v[202:205], v152 offset:4096
	ds_read_b128 v[206:209], v152 offset:5120
	ds_read_b128 v[210:213], v152 offset:6144
	ds_read_b128 v[214:217], v152 offset:7168
	global_load_lds_dwordx4 v[146:147], off
	v_lshl_add_u64 v[146:147], s[48:49], 0, v[140:141]
	s_add_i32 m0, s47, 0xe000
	s_nop 0
	global_load_lds_dwordx4 v[146:147], off
	s_waitcnt vmcnt(8)
	s_waitcnt lgkmcnt(0)
	s_barrier
	v_mfma_f32_16x16x32_bf16 v[126:129], v[154:157], v[186:189], v[126:129]
	v_mfma_f32_16x16x32_bf16 v[122:125], v[162:165], v[186:189], v[122:125]
	v_mfma_f32_16x16x32_bf16 v[118:121], v[154:157], v[194:197], v[118:121]
	v_mfma_f32_16x16x32_bf16 v[110:113], v[162:165], v[194:197], v[110:113]
	v_mfma_f32_16x16x32_bf16 v[102:105], v[154:157], v[202:205], v[102:105]
	v_mfma_f32_16x16x32_bf16 v[94:97], v[162:165], v[202:205], v[94:97]
	v_mfma_f32_16x16x32_bf16 v[86:89], v[154:157], v[210:213], v[86:89]
	v_mfma_f32_16x16x32_bf16 v[78:81], v[162:165], v[210:213], v[78:81]
	v_mfma_f32_16x16x32_bf16 v[126:129], v[158:161], v[190:193], v[126:129]
	v_mfma_f32_16x16x32_bf16 v[122:125], v[166:169], v[190:193], v[122:125]
	v_mfma_f32_16x16x32_bf16 v[118:121], v[158:161], v[198:201], v[118:121]
	v_mfma_f32_16x16x32_bf16 v[110:113], v[166:169], v[198:201], v[110:113]
	v_mfma_f32_16x16x32_bf16 v[102:105], v[158:161], v[206:209], v[102:105]
	v_mfma_f32_16x16x32_bf16 v[94:97], v[166:169], v[206:209], v[94:97]
	v_mfma_f32_16x16x32_bf16 v[86:89], v[158:161], v[214:217], v[86:89]
	v_mfma_f32_16x16x32_bf16 v[78:81], v[166:169], v[214:217], v[78:81]
	v_mfma_f32_16x16x32_bf16 v[114:117], v[170:173], v[186:189], v[114:117]
	v_mfma_f32_16x16x32_bf16 v[106:109], v[178:181], v[186:189], v[106:109]
	v_mfma_f32_16x16x32_bf16 v[98:101], v[170:173], v[194:197], v[98:101]
	v_mfma_f32_16x16x32_bf16 v[90:93], v[178:181], v[194:197], v[90:93]
	v_mfma_f32_16x16x32_bf16 v[82:85], v[170:173], v[202:205], v[82:85]
	v_mfma_f32_16x16x32_bf16 v[74:77], v[178:181], v[202:205], v[74:77]
	v_mfma_f32_16x16x32_bf16 v[70:73], v[170:173], v[210:213], v[70:73]
	v_mfma_f32_16x16x32_bf16 v[66:69], v[178:181], v[210:213], v[66:69]
	v_mfma_f32_16x16x32_bf16 v[114:117], v[174:177], v[190:193], v[114:117]
	v_mfma_f32_16x16x32_bf16 v[106:109], v[182:185], v[190:193], v[106:109]
	v_mfma_f32_16x16x32_bf16 v[98:101], v[174:177], v[198:201], v[98:101]
	v_mfma_f32_16x16x32_bf16 v[90:93], v[182:185], v[198:201], v[90:93]
	v_mfma_f32_16x16x32_bf16 v[82:85], v[174:177], v[206:209], v[82:85]
	v_mfma_f32_16x16x32_bf16 v[74:77], v[182:185], v[206:209], v[74:77]
	v_mfma_f32_16x16x32_bf16 v[70:73], v[174:177], v[214:217], v[70:73]
	v_mfma_f32_16x16x32_bf16 v[66:69], v[182:185], v[214:217], v[66:69]
	s_barrier
	s_add_i32 s79, s67, s54
	v_lshl_add_u64 v[146:147], s[50:51], 0, v[132:133]
	s_mov_b32 m0, s79
	ds_read_b128 v[186:189], v152 offset:16384
	ds_read_b128 v[190:193], v152 offset:17408
	ds_read_b128 v[194:197], v152 offset:18432
	ds_read_b128 v[198:201], v152 offset:19456
	ds_read_b128 v[202:205], v152 offset:20480
	ds_read_b128 v[206:209], v152 offset:21504
	ds_read_b128 v[210:213], v152 offset:22528
	ds_read_b128 v[214:217], v152 offset:23552
	global_load_lds_dwordx4 v[146:147], off
	s_add_i32 m0, s79, 0x2000
	s_add_u32 s80, s50, 0x100000
	v_lshl_add_u64 v[218:219], s[50:51], 0, v[136:137]
	s_addc_u32 s81, s51, 0
	s_add_i32 s79, s68, s54
	global_load_lds_dwordx4 v[218:219], off
	v_lshl_add_u64 v[220:221], s[80:81], 0, v[132:133]
	s_mov_b32 m0, s79
	v_lshl_add_u64 v[222:223], s[52:53], 0, v[134:135]
	global_load_lds_dwordx4 v[220:221], off
	v_lshl_add_u64 v[220:221], s[80:81], 0, v[136:137]
	s_add_i32 m0, s79, 0x2000
	s_nop 0
	global_load_lds_dwordx4 v[220:221], off
	v_lshl_add_u64 v[220:221], s[52:53], 0, v[130:131]
	s_mov_b32 m0, s47
	s_nop 0
	global_load_lds_dwordx4 v[220:221], off
	s_mov_b32 m0, s55
	s_nop 0
	global_load_lds_dwordx4 v[222:223], off
	s_waitcnt vmcnt(8)
	s_waitcnt lgkmcnt(0)
	s_barrier
	v_mfma_f32_16x16x32_bf16 v[62:65], v[154:157], v[186:189], v[62:65]
	v_mfma_f32_16x16x32_bf16 v[58:61], v[162:165], v[186:189], v[58:61]
	v_mfma_f32_16x16x32_bf16 v[54:57], v[154:157], v[194:197], v[54:57]
	v_mfma_f32_16x16x32_bf16 v[46:49], v[162:165], v[194:197], v[46:49]
	v_mfma_f32_16x16x32_bf16 v[38:41], v[154:157], v[202:205], v[38:41]
	v_mfma_f32_16x16x32_bf16 v[30:33], v[162:165], v[202:205], v[30:33]
	v_mfma_f32_16x16x32_bf16 v[22:25], v[154:157], v[210:213], v[22:25]
	v_mfma_f32_16x16x32_bf16 v[14:17], v[162:165], v[210:213], v[14:17]
	v_mfma_f32_16x16x32_bf16 v[62:65], v[158:161], v[190:193], v[62:65]
	v_mfma_f32_16x16x32_bf16 v[58:61], v[166:169], v[190:193], v[58:61]
	v_mfma_f32_16x16x32_bf16 v[54:57], v[158:161], v[198:201], v[54:57]
	v_mfma_f32_16x16x32_bf16 v[46:49], v[166:169], v[198:201], v[46:49]
	v_mfma_f32_16x16x32_bf16 v[38:41], v[158:161], v[206:209], v[38:41]
	v_mfma_f32_16x16x32_bf16 v[30:33], v[166:169], v[206:209], v[30:33]
	v_mfma_f32_16x16x32_bf16 v[22:25], v[158:161], v[214:217], v[22:25]
	v_mfma_f32_16x16x32_bf16 v[14:17], v[166:169], v[214:217], v[14:17]
	v_mfma_f32_16x16x32_bf16 v[50:53], v[170:173], v[186:189], v[50:53]
	v_mfma_f32_16x16x32_bf16 v[42:45], v[178:181], v[186:189], v[42:45]
	v_mfma_f32_16x16x32_bf16 v[34:37], v[170:173], v[194:197], v[34:37]
	v_mfma_f32_16x16x32_bf16 v[26:29], v[178:181], v[194:197], v[26:29]
	v_mfma_f32_16x16x32_bf16 v[18:21], v[170:173], v[202:205], v[18:21]
	v_mfma_f32_16x16x32_bf16 v[10:13], v[178:181], v[202:205], v[10:13]
	v_mfma_f32_16x16x32_bf16 v[6:9], v[170:173], v[210:213], v[6:9]
	v_mfma_f32_16x16x32_bf16 v[2:5], v[178:181], v[210:213], v[2:5]
	v_mfma_f32_16x16x32_bf16 v[50:53], v[174:177], v[190:193], v[50:53]
	v_mfma_f32_16x16x32_bf16 v[42:45], v[182:185], v[190:193], v[42:45]
	v_mfma_f32_16x16x32_bf16 v[34:37], v[174:177], v[198:201], v[34:37]
	v_mfma_f32_16x16x32_bf16 v[26:29], v[182:185], v[198:201], v[26:29]
	v_mfma_f32_16x16x32_bf16 v[18:21], v[174:177], v[206:209], v[18:21]
	v_mfma_f32_16x16x32_bf16 v[10:13], v[182:185], v[206:209], v[10:13]
	v_mfma_f32_16x16x32_bf16 v[6:9], v[174:177], v[214:217], v[6:9]
	v_mfma_f32_16x16x32_bf16 v[2:5], v[182:185], v[214:217], v[2:5]
	s_barrier
	s_add_i32 s79, 0, 0x18000
	v_add_u32_e32 v153, s79, v148
	s_add_i32 s80, 0, 0x1c000
	ds_read_b128 v[154:157], v153
	ds_read_b128 v[158:161], v153 offset:1024
	ds_read_b128 v[162:165], v153 offset:2048
	ds_read_b128 v[166:169], v153 offset:3072
	v_add_u32_e32 v153, s80, v148
	ds_read_b128 v[170:173], v153
	ds_read_b128 v[174:177], v153 offset:1024
	ds_read_b128 v[178:181], v153 offset:2048
	ds_read_b128 v[182:185], v153 offset:3072
	s_add_u32 s52, s52, 0x100000
	s_addc_u32 s53, s53, 0
	s_mov_b32 m0, s56
	v_lshl_add_u64 v[224:225], s[52:53], 0, v[130:131]
	ds_read_b128 v[186:189], v152 offset:32768
	ds_read_b128 v[190:193], v152 offset:33792
	ds_read_b128 v[194:197], v152 offset:34816
	ds_read_b128 v[198:201], v152 offset:35840
	ds_read_b128 v[202:205], v152 offset:36864
	ds_read_b128 v[206:209], v152 offset:37888
	ds_read_b128 v[210:213], v152 offset:38912
	ds_read_b128 v[214:217], v152 offset:39936
	global_load_lds_dwordx4 v[224:225], off
	v_lshl_add_u64 v[224:225], s[52:53], 0, v[134:135]
	s_mov_b32 m0, s57
	s_nop 0
	global_load_lds_dwordx4 v[224:225], off
	s_waitcnt vmcnt(8)
	s_waitcnt lgkmcnt(0)
	s_barrier
	v_mfma_f32_16x16x32_bf16 v[126:129], v[154:157], v[186:189], v[126:129]
	v_mfma_f32_16x16x32_bf16 v[122:125], v[162:165], v[186:189], v[122:125]
	v_mfma_f32_16x16x32_bf16 v[118:121], v[154:157], v[194:197], v[118:121]
	v_mfma_f32_16x16x32_bf16 v[110:113], v[162:165], v[194:197], v[110:113]
	v_mfma_f32_16x16x32_bf16 v[102:105], v[154:157], v[202:205], v[102:105]
	v_mfma_f32_16x16x32_bf16 v[94:97], v[162:165], v[202:205], v[94:97]
	v_mfma_f32_16x16x32_bf16 v[86:89], v[154:157], v[210:213], v[86:89]
	v_mfma_f32_16x16x32_bf16 v[78:81], v[162:165], v[210:213], v[78:81]
	v_mfma_f32_16x16x32_bf16 v[126:129], v[158:161], v[190:193], v[126:129]
	v_mfma_f32_16x16x32_bf16 v[122:125], v[166:169], v[190:193], v[122:125]
	v_mfma_f32_16x16x32_bf16 v[118:121], v[158:161], v[198:201], v[118:121]
	v_mfma_f32_16x16x32_bf16 v[110:113], v[166:169], v[198:201], v[110:113]
	v_mfma_f32_16x16x32_bf16 v[102:105], v[158:161], v[206:209], v[102:105]
	v_mfma_f32_16x16x32_bf16 v[94:97], v[166:169], v[206:209], v[94:97]
	v_mfma_f32_16x16x32_bf16 v[86:89], v[158:161], v[214:217], v[86:89]
	v_mfma_f32_16x16x32_bf16 v[78:81], v[166:169], v[214:217], v[78:81]
	v_mfma_f32_16x16x32_bf16 v[114:117], v[170:173], v[186:189], v[114:117]
	v_mfma_f32_16x16x32_bf16 v[106:109], v[178:181], v[186:189], v[106:109]
	v_mfma_f32_16x16x32_bf16 v[98:101], v[170:173], v[194:197], v[98:101]
	v_mfma_f32_16x16x32_bf16 v[90:93], v[178:181], v[194:197], v[90:93]
	v_mfma_f32_16x16x32_bf16 v[82:85], v[170:173], v[202:205], v[82:85]
	v_mfma_f32_16x16x32_bf16 v[74:77], v[178:181], v[202:205], v[74:77]
	v_mfma_f32_16x16x32_bf16 v[70:73], v[170:173], v[210:213], v[70:73]
	v_mfma_f32_16x16x32_bf16 v[66:69], v[178:181], v[210:213], v[66:69]
	v_mfma_f32_16x16x32_bf16 v[114:117], v[174:177], v[190:193], v[114:117]
	v_mfma_f32_16x16x32_bf16 v[106:109], v[182:185], v[190:193], v[106:109]
	v_mfma_f32_16x16x32_bf16 v[98:101], v[174:177], v[198:201], v[98:101]
	v_mfma_f32_16x16x32_bf16 v[90:93], v[182:185], v[198:201], v[90:93]
	v_mfma_f32_16x16x32_bf16 v[82:85], v[174:177], v[206:209], v[82:85]
	v_mfma_f32_16x16x32_bf16 v[74:77], v[182:185], v[206:209], v[74:77]
	v_mfma_f32_16x16x32_bf16 v[70:73], v[174:177], v[214:217], v[70:73]
	v_mfma_f32_16x16x32_bf16 v[66:69], v[182:185], v[214:217], v[66:69]
	s_barrier
	s_add_i32 s52, s79, s54
	v_lshl_add_u64 v[146:147], v[146:147], 0, s[16:17]
	s_mov_b32 m0, s52
	ds_read_b128 v[186:189], v152 offset:49152
	ds_read_b128 v[190:193], v152 offset:50176
	ds_read_b128 v[194:197], v152 offset:51200
	ds_read_b128 v[198:201], v152 offset:52224
	ds_read_b128 v[202:205], v152 offset:53248
	ds_read_b128 v[206:209], v152 offset:54272
	ds_read_b128 v[210:213], v152 offset:55296
	ds_read_b128 v[214:217], v152 offset:56320
	global_load_lds_dwordx4 v[146:147], off
	s_add_i32 m0, s52, 0x2000
	s_add_u32 s50, s50, 0x100080
	v_lshl_add_u64 v[146:147], v[218:219], 0, s[16:17]
	s_addc_u32 s51, s51, 0
	s_add_i32 s52, s80, s54
	global_load_lds_dwordx4 v[146:147], off
	v_lshl_add_u64 v[146:147], s[50:51], 0, v[132:133]
	s_mov_b32 m0, s52
	s_nop 0
	global_load_lds_dwordx4 v[146:147], off
	v_lshl_add_u64 v[146:147], s[50:51], 0, v[136:137]
	s_add_i32 m0, s52, 0x2000
	s_nop 0
	global_load_lds_dwordx4 v[146:147], off
	v_lshl_add_u64 v[146:147], v[220:221], 0, s[16:17]
	s_mov_b32 m0, s59
	s_nop 0
	global_load_lds_dwordx4 v[146:147], off
	v_lshl_add_u64 v[146:147], v[222:223], 0, s[16:17]
	s_mov_b32 m0, s61
	s_nop 0
	global_load_lds_dwordx4 v[146:147], off
	s_waitcnt vmcnt(8)
	s_waitcnt lgkmcnt(0)
	s_barrier
	v_mfma_f32_16x16x32_bf16 v[62:65], v[154:157], v[186:189], v[62:65]
	v_mfma_f32_16x16x32_bf16 v[58:61], v[162:165], v[186:189], v[58:61]
	v_mfma_f32_16x16x32_bf16 v[54:57], v[154:157], v[194:197], v[54:57]
	v_mfma_f32_16x16x32_bf16 v[46:49], v[162:165], v[194:197], v[46:49]
	v_mfma_f32_16x16x32_bf16 v[38:41], v[154:157], v[202:205], v[38:41]
	v_mfma_f32_16x16x32_bf16 v[30:33], v[162:165], v[202:205], v[30:33]
	v_mfma_f32_16x16x32_bf16 v[22:25], v[154:157], v[210:213], v[22:25]
	v_mfma_f32_16x16x32_bf16 v[14:17], v[162:165], v[210:213], v[14:17]
	v_mfma_f32_16x16x32_bf16 v[62:65], v[158:161], v[190:193], v[62:65]
	v_mfma_f32_16x16x32_bf16 v[58:61], v[166:169], v[190:193], v[58:61]
	v_mfma_f32_16x16x32_bf16 v[54:57], v[158:161], v[198:201], v[54:57]
	v_mfma_f32_16x16x32_bf16 v[46:49], v[166:169], v[198:201], v[46:49]
	v_mfma_f32_16x16x32_bf16 v[38:41], v[158:161], v[206:209], v[38:41]
	v_mfma_f32_16x16x32_bf16 v[30:33], v[166:169], v[206:209], v[30:33]
	v_mfma_f32_16x16x32_bf16 v[22:25], v[158:161], v[214:217], v[22:25]
	v_mfma_f32_16x16x32_bf16 v[14:17], v[166:169], v[214:217], v[14:17]
	v_mfma_f32_16x16x32_bf16 v[50:53], v[170:173], v[186:189], v[50:53]
	v_mfma_f32_16x16x32_bf16 v[42:45], v[178:181], v[186:189], v[42:45]
	v_mfma_f32_16x16x32_bf16 v[34:37], v[170:173], v[194:197], v[34:37]
	v_mfma_f32_16x16x32_bf16 v[26:29], v[178:181], v[194:197], v[26:29]
	v_mfma_f32_16x16x32_bf16 v[18:21], v[170:173], v[202:205], v[18:21]
	v_mfma_f32_16x16x32_bf16 v[10:13], v[178:181], v[202:205], v[10:13]
	v_mfma_f32_16x16x32_bf16 v[6:9], v[170:173], v[210:213], v[6:9]
	v_mfma_f32_16x16x32_bf16 v[2:5], v[178:181], v[210:213], v[2:5]
	v_mfma_f32_16x16x32_bf16 v[50:53], v[174:177], v[190:193], v[50:53]
	v_mfma_f32_16x16x32_bf16 v[42:45], v[182:185], v[190:193], v[42:45]
	v_mfma_f32_16x16x32_bf16 v[34:37], v[174:177], v[198:201], v[34:37]
	v_mfma_f32_16x16x32_bf16 v[26:29], v[182:185], v[198:201], v[26:29]
	v_mfma_f32_16x16x32_bf16 v[18:21], v[174:177], v[206:209], v[18:21]
	v_mfma_f32_16x16x32_bf16 v[10:13], v[182:185], v[206:209], v[10:13]
	v_mfma_f32_16x16x32_bf16 v[6:9], v[174:177], v[214:217], v[6:9]
	v_mfma_f32_16x16x32_bf16 v[2:5], v[182:185], v[214:217], v[2:5]
	s_barrier
	s_add_i32 s78, s78, 2
	s_add_u32 s48, s48, 0x100
	s_addc_u32 s49, s49, 0
	s_add_u32 s29, s29, 0x100
	s_addc_u32 s41, s41, 0
	s_cmp_gt_u32 s78, 61
	s_cbranch_scc0 .LBB0_886
	s_setprio 0
	s_and_b64 vcc, exec, s[18:19]
	s_cbranch_vccz .LBB0_889
	s_barrier

.Lsp_p11:
.LBB0_1015:
	ds_read_b128 v[146:149], v156
	ds_read_b128 v[150:153], v156 offset:1024
	ds_read_b128 v[160:163], v156 offset:2048
	ds_read_b128 v[164:167], v156 offset:3072
	ds_read_b128 v[168:171], v157
	ds_read_b128 v[172:175], v157 offset:1024
	ds_read_b128 v[176:179], v157 offset:2048
	ds_read_b128 v[180:183], v157 offset:3072
	s_add_u32 s44, s42, 0xfff80080
	s_addc_u32 s45, s43, -1
	s_cmp_eq_u32 s67, 28
	s_cselect_b32 s47, s8, s45
	s_cselect_b32 s46, s9, s44
	s_cselect_b32 s45, s21, s66
	s_cselect_b32 s44, s23, s61
	v_lshl_add_u64 v[216:217], s[42:43], 0, v[138:139]
	s_add_i32 m0, s41, 0xc000
	ds_read_b128 v[184:187], v158
	ds_read_b128 v[188:191], v158 offset:1024
	ds_read_b128 v[192:195], v158 offset:2048
	ds_read_b128 v[196:199], v158 offset:3072
	ds_read_b128 v[200:203], v158 offset:4096
	ds_read_b128 v[204:207], v158 offset:5120
	ds_read_b128 v[208:211], v158 offset:6144
	ds_read_b128 v[212:215], v158 offset:7168
	global_load_lds_dwordx4 v[216:217], off
	v_lshl_add_u64 v[216:217], s[42:43], 0, v[140:141]
	s_add_i32 m0, s41, 0xe000
	s_nop 0
	global_load_lds_dwordx4 v[216:217], off
	s_waitcnt vmcnt(8)
	s_waitcnt lgkmcnt(0)
	s_barrier
	v_mfma_i32_16x16x64_i8 v[126:129], v[146:149], v[184:187], v[126:129]
	v_mfma_i32_16x16x64_i8 v[122:125], v[160:163], v[184:187], v[122:125]
	v_mfma_i32_16x16x64_i8 v[110:113], v[146:149], v[192:195], v[110:113]
	v_mfma_i32_16x16x64_i8 v[106:109], v[160:163], v[192:195], v[106:109]
	v_mfma_i32_16x16x64_i8 v[94:97], v[146:149], v[200:203], v[94:97]
	v_mfma_i32_16x16x64_i8 v[90:93], v[160:163], v[200:203], v[90:93]
	v_mfma_i32_16x16x64_i8 v[78:81], v[146:149], v[208:211], v[78:81]
	v_mfma_i32_16x16x64_i8 v[74:77], v[160:163], v[208:211], v[74:77]
	v_mfma_i32_16x16x64_i8 v[126:129], v[150:153], v[188:191], v[126:129]
	v_mfma_i32_16x16x64_i8 v[122:125], v[164:167], v[188:191], v[122:125]
	v_mfma_i32_16x16x64_i8 v[110:113], v[150:153], v[196:199], v[110:113]
	v_mfma_i32_16x16x64_i8 v[106:109], v[164:167], v[196:199], v[106:109]
	v_mfma_i32_16x16x64_i8 v[94:97], v[150:153], v[204:207], v[94:97]
	v_mfma_i32_16x16x64_i8 v[90:93], v[164:167], v[204:207], v[90:93]
	v_mfma_i32_16x16x64_i8 v[78:81], v[150:153], v[212:215], v[78:81]
	v_mfma_i32_16x16x64_i8 v[74:77], v[164:167], v[212:215], v[74:77]
	v_mfma_i32_16x16x64_i8 v[118:121], v[168:171], v[184:187], v[118:121]
	v_mfma_i32_16x16x64_i8 v[114:117], v[176:179], v[184:187], v[114:117]
	v_mfma_i32_16x16x64_i8 v[102:105], v[168:171], v[192:195], v[102:105]
	v_mfma_i32_16x16x64_i8 v[98:101], v[176:179], v[192:195], v[98:101]
	v_mfma_i32_16x16x64_i8 v[86:89], v[168:171], v[200:203], v[86:89]
	v_mfma_i32_16x16x64_i8 v[82:85], v[176:179], v[200:203], v[82:85]
	v_mfma_i32_16x16x64_i8 v[70:73], v[168:171], v[208:211], v[70:73]
	v_mfma_i32_16x16x64_i8 v[66:69], v[176:179], v[208:211], v[66:69]
	v_mfma_i32_16x16x64_i8 v[118:121], v[172:175], v[188:191], v[118:121]
	v_mfma_i32_16x16x64_i8 v[114:117], v[180:183], v[188:191], v[114:117]
	v_mfma_i32_16x16x64_i8 v[102:105], v[172:175], v[196:199], v[102:105]
	v_mfma_i32_16x16x64_i8 v[98:101], v[180:183], v[196:199], v[98:101]
	v_mfma_i32_16x16x64_i8 v[86:89], v[172:175], v[204:207], v[86:89]
	v_mfma_i32_16x16x64_i8 v[82:85], v[180:183], v[204:207], v[82:85]
	v_mfma_i32_16x16x64_i8 v[70:73], v[172:175], v[212:215], v[70:73]
	v_mfma_i32_16x16x64_i8 v[66:69], v[180:183], v[212:215], v[66:69]
	s_barrier
	s_add_i32 s68, s56, s19
	v_lshl_add_u64 v[216:217], s[44:45], 0, v[134:135]
	s_mov_b32 m0, s68
	ds_read_b128 v[184:187], v158 offset:16384
	ds_read_b128 v[188:191], v158 offset:17408
	ds_read_b128 v[192:195], v158 offset:18432
	ds_read_b128 v[196:199], v158 offset:19456
	ds_read_b128 v[200:203], v158 offset:20480
	ds_read_b128 v[204:207], v158 offset:21504
	ds_read_b128 v[208:211], v158 offset:22528
	ds_read_b128 v[212:215], v158 offset:23552
	global_load_lds_dwordx4 v[216:217], off
	s_add_i32 m0, s68, 0x2000
	s_add_u32 s68, s44, 0x80000
	v_lshl_add_u64 v[218:219], s[44:45], 0, v[130:131]
	s_addc_u32 s69, s45, 0
	s_add_i32 s72, s57, s19
	global_load_lds_dwordx4 v[218:219], off
	v_lshl_add_u64 v[220:221], s[68:69], 0, v[134:135]
	s_mov_b32 m0, s72
	v_lshl_add_u64 v[222:223], s[46:47], 0, v[132:133]
	global_load_lds_dwordx4 v[220:221], off
	v_lshl_add_u64 v[220:221], s[68:69], 0, v[130:131]
	s_add_i32 m0, s72, 0x2000
	s_nop 0
	global_load_lds_dwordx4 v[220:221], off
	v_lshl_add_u64 v[220:221], s[46:47], 0, v[136:137]
	s_mov_b32 m0, s41
	s_nop 0
	global_load_lds_dwordx4 v[220:221], off
	s_mov_b32 m0, s49
	s_nop 0
	global_load_lds_dwordx4 v[222:223], off
	s_waitcnt vmcnt(8)
	s_waitcnt lgkmcnt(0)
	s_barrier
	v_mfma_i32_16x16x64_i8 v[62:65], v[146:149], v[184:187], v[62:65]
	v_mfma_i32_16x16x64_i8 v[58:61], v[160:163], v[184:187], v[58:61]
	v_mfma_i32_16x16x64_i8 v[46:49], v[146:149], v[192:195], v[46:49]
	v_mfma_i32_16x16x64_i8 v[42:45], v[160:163], v[192:195], v[42:45]
	v_mfma_i32_16x16x64_i8 v[30:33], v[146:149], v[200:203], v[30:33]
	v_mfma_i32_16x16x64_i8 v[26:29], v[160:163], v[200:203], v[26:29]
	v_mfma_i32_16x16x64_i8 v[14:17], v[146:149], v[208:211], v[14:17]
	v_mfma_i32_16x16x64_i8 v[10:13], v[160:163], v[208:211], v[10:13]
	v_mfma_i32_16x16x64_i8 v[62:65], v[150:153], v[188:191], v[62:65]
	v_mfma_i32_16x16x64_i8 v[58:61], v[164:167], v[188:191], v[58:61]
	v_mfma_i32_16x16x64_i8 v[46:49], v[150:153], v[196:199], v[46:49]
	v_mfma_i32_16x16x64_i8 v[42:45], v[164:167], v[196:199], v[42:45]
	v_mfma_i32_16x16x64_i8 v[30:33], v[150:153], v[204:207], v[30:33]
	v_mfma_i32_16x16x64_i8 v[26:29], v[164:167], v[204:207], v[26:29]
	v_mfma_i32_16x16x64_i8 v[14:17], v[150:153], v[212:215], v[14:17]
	v_mfma_i32_16x16x64_i8 v[10:13], v[164:167], v[212:215], v[10:13]
	v_mfma_i32_16x16x64_i8 v[54:57], v[168:171], v[184:187], v[54:57]
	v_mfma_i32_16x16x64_i8 v[50:53], v[176:179], v[184:187], v[50:53]
	v_mfma_i32_16x16x64_i8 v[38:41], v[168:171], v[192:195], v[38:41]
	v_mfma_i32_16x16x64_i8 v[34:37], v[176:179], v[192:195], v[34:37]
	v_mfma_i32_16x16x64_i8 v[22:25], v[168:171], v[200:203], v[22:25]
	v_mfma_i32_16x16x64_i8 v[18:21], v[176:179], v[200:203], v[18:21]
	v_mfma_i32_16x16x64_i8 v[6:9], v[168:171], v[208:211], v[6:9]
	v_mfma_i32_16x16x64_i8 v[2:5], v[176:179], v[208:211], v[2:5]
	v_mfma_i32_16x16x64_i8 v[54:57], v[172:175], v[188:191], v[54:57]
	v_mfma_i32_16x16x64_i8 v[50:53], v[180:183], v[188:191], v[50:53]
	v_mfma_i32_16x16x64_i8 v[38:41], v[172:175], v[196:199], v[38:41]
	v_mfma_i32_16x16x64_i8 v[34:37], v[180:183], v[196:199], v[34:37]
	v_mfma_i32_16x16x64_i8 v[22:25], v[172:175], v[204:207], v[22:25]
	v_mfma_i32_16x16x64_i8 v[18:21], v[180:183], v[204:207], v[18:21]
	v_mfma_i32_16x16x64_i8 v[6:9], v[172:175], v[212:215], v[6:9]
	v_mfma_i32_16x16x64_i8 v[2:5], v[180:183], v[212:215], v[2:5]
	s_barrier
	s_add_i32 s68, 0, 0x18000
	v_add_u32_e32 v159, s68, v154
	s_add_i32 s69, 0, 0x1c000
	ds_read_b128 v[146:149], v159
	ds_read_b128 v[150:153], v159 offset:1024
	ds_read_b128 v[160:163], v159 offset:2048
	ds_read_b128 v[164:167], v159 offset:3072
	v_add_u32_e32 v159, s69, v154
	ds_read_b128 v[168:171], v159
	ds_read_b128 v[172:175], v159 offset:1024
	ds_read_b128 v[176:179], v159 offset:2048
	ds_read_b128 v[180:183], v159 offset:3072
	s_add_u32 s46, s46, 0x80000
	s_addc_u32 s47, s47, 0
	s_mov_b32 m0, s50
	v_lshl_add_u64 v[224:225], s[46:47], 0, v[136:137]
	ds_read_b128 v[184:187], v158 offset:32768
	ds_read_b128 v[188:191], v158 offset:33792
	ds_read_b128 v[192:195], v158 offset:34816
	ds_read_b128 v[196:199], v158 offset:35840
	ds_read_b128 v[200:203], v158 offset:36864
	ds_read_b128 v[204:207], v158 offset:37888
	ds_read_b128 v[208:211], v158 offset:38912
	ds_read_b128 v[212:215], v158 offset:39936
	global_load_lds_dwordx4 v[224:225], off
	v_lshl_add_u64 v[224:225], s[46:47], 0, v[132:133]
	s_mov_b32 m0, s51
	s_nop 0
	global_load_lds_dwordx4 v[224:225], off
	s_waitcnt vmcnt(8)
	s_waitcnt lgkmcnt(0)
	s_barrier
	v_mfma_i32_16x16x64_i8 v[126:129], v[146:149], v[184:187], v[126:129]
	v_mfma_i32_16x16x64_i8 v[122:125], v[160:163], v[184:187], v[122:125]
	v_mfma_i32_16x16x64_i8 v[110:113], v[146:149], v[192:195], v[110:113]
	v_mfma_i32_16x16x64_i8 v[106:109], v[160:163], v[192:195], v[106:109]
	v_mfma_i32_16x16x64_i8 v[94:97], v[146:149], v[200:203], v[94:97]
	v_mfma_i32_16x16x64_i8 v[90:93], v[160:163], v[200:203], v[90:93]
	v_mfma_i32_16x16x64_i8 v[78:81], v[146:149], v[208:211], v[78:81]
	v_mfma_i32_16x16x64_i8 v[74:77], v[160:163], v[208:211], v[74:77]
	v_mfma_i32_16x16x64_i8 v[126:129], v[150:153], v[188:191], v[126:129]
	v_mfma_i32_16x16x64_i8 v[122:125], v[164:167], v[188:191], v[122:125]
	v_mfma_i32_16x16x64_i8 v[110:113], v[150:153], v[196:199], v[110:113]
	v_mfma_i32_16x16x64_i8 v[106:109], v[164:167], v[196:199], v[106:109]
	v_mfma_i32_16x16x64_i8 v[94:97], v[150:153], v[204:207], v[94:97]
	v_mfma_i32_16x16x64_i8 v[90:93], v[164:167], v[204:207], v[90:93]
	v_mfma_i32_16x16x64_i8 v[78:81], v[150:153], v[212:215], v[78:81]
	v_mfma_i32_16x16x64_i8 v[74:77], v[164:167], v[212:215], v[74:77]
	v_mfma_i32_16x16x64_i8 v[118:121], v[168:171], v[184:187], v[118:121]
	v_mfma_i32_16x16x64_i8 v[114:117], v[176:179], v[184:187], v[114:117]
	v_mfma_i32_16x16x64_i8 v[102:105], v[168:171], v[192:195], v[102:105]
	v_mfma_i32_16x16x64_i8 v[98:101], v[176:179], v[192:195], v[98:101]
	v_mfma_i32_16x16x64_i8 v[86:89], v[168:171], v[200:203], v[86:89]
	v_mfma_i32_16x16x64_i8 v[82:85], v[176:179], v[200:203], v[82:85]
	v_mfma_i32_16x16x64_i8 v[70:73], v[168:171], v[208:211], v[70:73]
	v_mfma_i32_16x16x64_i8 v[66:69], v[176:179], v[208:211], v[66:69]
	v_mfma_i32_16x16x64_i8 v[118:121], v[172:175], v[188:191], v[118:121]
	v_mfma_i32_16x16x64_i8 v[114:117], v[180:183], v[188:191], v[114:117]
	v_mfma_i32_16x16x64_i8 v[102:105], v[172:175], v[196:199], v[102:105]
	v_mfma_i32_16x16x64_i8 v[98:101], v[180:183], v[196:199], v[98:101]
	v_mfma_i32_16x16x64_i8 v[86:89], v[172:175], v[204:207], v[86:89]
	v_mfma_i32_16x16x64_i8 v[82:85], v[180:183], v[204:207], v[82:85]
	v_mfma_i32_16x16x64_i8 v[70:73], v[172:175], v[212:215], v[70:73]
	v_mfma_i32_16x16x64_i8 v[66:69], v[180:183], v[212:215], v[66:69]
	s_barrier
	s_add_i32 s46, s68, s19
	v_lshl_add_u64 v[216:217], v[216:217], 0, s[4:5]
	s_mov_b32 m0, s46
	ds_read_b128 v[184:187], v158 offset:49152
	ds_read_b128 v[188:191], v158 offset:50176
	ds_read_b128 v[192:195], v158 offset:51200
	ds_read_b128 v[196:199], v158 offset:52224
	ds_read_b128 v[200:203], v158 offset:53248
	ds_read_b128 v[204:207], v158 offset:54272
	ds_read_b128 v[208:211], v158 offset:55296
	ds_read_b128 v[212:215], v158 offset:56320
	global_load_lds_dwordx4 v[216:217], off
	s_add_i32 m0, s46, 0x2000
	s_add_u32 s44, s44, 0x80080
	v_lshl_add_u64 v[216:217], v[218:219], 0, s[4:5]
	s_addc_u32 s45, s45, 0
	s_add_i32 s46, s69, s19
	global_load_lds_dwordx4 v[216:217], off
	v_lshl_add_u64 v[216:217], s[44:45], 0, v[134:135]
	s_mov_b32 m0, s46
	s_nop 0
	global_load_lds_dwordx4 v[216:217], off
	v_lshl_add_u64 v[216:217], s[44:45], 0, v[130:131]
	s_add_i32 m0, s46, 0x2000
	s_nop 0
	global_load_lds_dwordx4 v[216:217], off
	v_lshl_add_u64 v[216:217], v[220:221], 0, s[4:5]
	s_mov_b32 m0, s53
	s_nop 0
	global_load_lds_dwordx4 v[216:217], off
	v_lshl_add_u64 v[216:217], v[222:223], 0, s[4:5]
	s_mov_b32 m0, s54
	s_nop 0
	global_load_lds_dwordx4 v[216:217], off
	s_waitcnt vmcnt(8)
	s_waitcnt lgkmcnt(0)
	s_barrier
	v_mfma_i32_16x16x64_i8 v[62:65], v[146:149], v[184:187], v[62:65]
	v_mfma_i32_16x16x64_i8 v[58:61], v[160:163], v[184:187], v[58:61]
	v_mfma_i32_16x16x64_i8 v[46:49], v[146:149], v[192:195], v[46:49]
	v_mfma_i32_16x16x64_i8 v[42:45], v[160:163], v[192:195], v[42:45]
	v_mfma_i32_16x16x64_i8 v[30:33], v[146:149], v[200:203], v[30:33]
	v_mfma_i32_16x16x64_i8 v[26:29], v[160:163], v[200:203], v[26:29]
	v_mfma_i32_16x16x64_i8 v[14:17], v[146:149], v[208:211], v[14:17]
	v_mfma_i32_16x16x64_i8 v[10:13], v[160:163], v[208:211], v[10:13]
	v_mfma_i32_16x16x64_i8 v[62:65], v[150:153], v[188:191], v[62:65]
	v_mfma_i32_16x16x64_i8 v[58:61], v[164:167], v[188:191], v[58:61]
	v_mfma_i32_16x16x64_i8 v[46:49], v[150:153], v[196:199], v[46:49]
	v_mfma_i32_16x16x64_i8 v[42:45], v[164:167], v[196:199], v[42:45]
	v_mfma_i32_16x16x64_i8 v[30:33], v[150:153], v[204:207], v[30:33]
	v_mfma_i32_16x16x64_i8 v[26:29], v[164:167], v[204:207], v[26:29]
	v_mfma_i32_16x16x64_i8 v[14:17], v[150:153], v[212:215], v[14:17]
	v_mfma_i32_16x16x64_i8 v[10:13], v[164:167], v[212:215], v[10:13]
	v_mfma_i32_16x16x64_i8 v[54:57], v[168:171], v[184:187], v[54:57]
	v_mfma_i32_16x16x64_i8 v[50:53], v[176:179], v[184:187], v[50:53]
	v_mfma_i32_16x16x64_i8 v[38:41], v[168:171], v[192:195], v[38:41]
	v_mfma_i32_16x16x64_i8 v[34:37], v[176:179], v[192:195], v[34:37]
	v_mfma_i32_16x16x64_i8 v[22:25], v[168:171], v[200:203], v[22:25]
	v_mfma_i32_16x16x64_i8 v[18:21], v[176:179], v[200:203], v[18:21]
	v_mfma_i32_16x16x64_i8 v[6:9], v[168:171], v[208:211], v[6:9]
	v_mfma_i32_16x16x64_i8 v[2:5], v[176:179], v[208:211], v[2:5]
	v_mfma_i32_16x16x64_i8 v[54:57], v[172:175], v[188:191], v[54:57]
	v_mfma_i32_16x16x64_i8 v[50:53], v[180:183], v[188:191], v[50:53]
	v_mfma_i32_16x16x64_i8 v[38:41], v[172:175], v[196:199], v[38:41]
	v_mfma_i32_16x16x64_i8 v[34:37], v[180:183], v[196:199], v[34:37]
	v_mfma_i32_16x16x64_i8 v[22:25], v[172:175], v[204:207], v[22:25]
	v_mfma_i32_16x16x64_i8 v[18:21], v[180:183], v[204:207], v[18:21]
	v_mfma_i32_16x16x64_i8 v[6:9], v[172:175], v[212:215], v[6:9]
	v_mfma_i32_16x16x64_i8 v[2:5], v[180:183], v[212:215], v[2:5]
	s_barrier
	s_add_i32 s67, s67, 2
	s_add_u32 s42, s42, 0x100
	s_addc_u32 s43, s43, 0
	s_add_u32 s61, s61, 0x100
	s_addc_u32 s66, s66, 0
	s_cmp_gt_u32 s67, 29
	s_cbranch_scc0 .LBB0_1015
	s_setprio 0
	s_and_b64 vcc, exec, s[12:13]
	s_cbranch_vccz .LBB0_1018
	s_barrier

.Lsp_p13:
.LBB0_1166:
	ds_read_b128 v[104:107], v167
	ds_read_b128 v[108:111], v167 offset:1024
	ds_read_b128 v[112:115], v167 offset:2048
	ds_read_b128 v[120:123], v167 offset:3072
	ds_read_b128 v[158:161], v168
	ds_read_b128 v[170:173], v168 offset:1024
	ds_read_b128 v[174:177], v168 offset:2048
	ds_read_b128 v[178:181], v168 offset:3072
	s_add_u32 s26, s6, 0xffea8080
	s_addc_u32 s27, s7, -1
	s_cmpk_eq_i32 s55, 0x52
	s_cselect_b32 s29, s23, s27
	s_cselect_b32 s28, s22, s26
	s_cselect_b32 s27, s25, s9
	s_cselect_b32 s26, s24, s8
	v_lshl_add_u64 v[214:215], s[6:7], 0, v[152:153]
	s_add_i32 m0, s38, 0xc000
	ds_read_b128 v[182:185], v169
	ds_read_b128 v[186:189], v169 offset:1024
	ds_read_b128 v[190:193], v169 offset:2048
	ds_read_b128 v[194:197], v169 offset:3072
	ds_read_b128 v[198:201], v169 offset:4096
	ds_read_b128 v[202:205], v169 offset:5120
	ds_read_b128 v[206:209], v169 offset:6144
	ds_read_b128 v[210:213], v169 offset:7168
	global_load_lds_dwordx4 v[214:215], off
	v_lshl_add_u64 v[214:215], s[6:7], 0, v[154:155]
	s_add_i32 m0, s38, 0xe000
	s_nop 0
	global_load_lds_dwordx4 v[214:215], off
	s_waitcnt vmcnt(8)
	s_waitcnt lgkmcnt(0)
	s_barrier
	v_mfma_i32_16x16x64_i8 v[140:143], v[104:107], v[182:185], v[140:143]
	v_mfma_i32_16x16x64_i8 v[136:139], v[112:115], v[182:185], v[136:139]
	v_mfma_i32_16x16x64_i8 v[124:127], v[104:107], v[190:193], v[124:127]
	v_mfma_i32_16x16x64_i8 v[116:119], v[112:115], v[190:193], v[116:119]
	v_mfma_i32_16x16x64_i8 v[92:95], v[104:107], v[198:201], v[92:95]
	v_mfma_i32_16x16x64_i8 v[88:91], v[112:115], v[198:201], v[88:91]
	v_mfma_i32_16x16x64_i8 v[76:79], v[104:107], v[206:209], v[76:79]
	v_mfma_i32_16x16x64_i8 v[72:75], v[112:115], v[206:209], v[72:75]
	v_mfma_i32_16x16x64_i8 v[140:143], v[108:111], v[186:189], v[140:143]
	v_mfma_i32_16x16x64_i8 v[136:139], v[120:123], v[186:189], v[136:139]
	v_mfma_i32_16x16x64_i8 v[124:127], v[108:111], v[194:197], v[124:127]
	v_mfma_i32_16x16x64_i8 v[116:119], v[120:123], v[194:197], v[116:119]
	v_mfma_i32_16x16x64_i8 v[92:95], v[108:111], v[202:205], v[92:95]
	v_mfma_i32_16x16x64_i8 v[88:91], v[120:123], v[202:205], v[88:91]
	v_mfma_i32_16x16x64_i8 v[76:79], v[108:111], v[210:213], v[76:79]
	v_mfma_i32_16x16x64_i8 v[72:75], v[120:123], v[210:213], v[72:75]
	v_mfma_i32_16x16x64_i8 v[132:135], v[158:161], v[182:185], v[132:135]
	v_mfma_i32_16x16x64_i8 v[128:131], v[174:177], v[182:185], v[128:131]
	v_mfma_i32_16x16x64_i8 v[100:103], v[158:161], v[190:193], v[100:103]
	v_mfma_i32_16x16x64_i8 v[96:99], v[174:177], v[190:193], v[96:99]
	v_mfma_i32_16x16x64_i8 v[84:87], v[158:161], v[198:201], v[84:87]
	v_mfma_i32_16x16x64_i8 v[80:83], v[174:177], v[198:201], v[80:83]
	v_mfma_i32_16x16x64_i8 v[68:71], v[158:161], v[206:209], v[68:71]
	v_mfma_i32_16x16x64_i8 v[64:67], v[174:177], v[206:209], v[64:67]
	v_mfma_i32_16x16x64_i8 v[132:135], v[170:173], v[186:189], v[132:135]
	v_mfma_i32_16x16x64_i8 v[128:131], v[178:181], v[186:189], v[128:131]
	v_mfma_i32_16x16x64_i8 v[100:103], v[170:173], v[194:197], v[100:103]
	v_mfma_i32_16x16x64_i8 v[96:99], v[178:181], v[194:197], v[96:99]
	v_mfma_i32_16x16x64_i8 v[84:87], v[170:173], v[202:205], v[84:87]
	v_mfma_i32_16x16x64_i8 v[80:83], v[178:181], v[202:205], v[80:83]
	v_mfma_i32_16x16x64_i8 v[68:71], v[170:173], v[210:213], v[68:71]
	v_mfma_i32_16x16x64_i8 v[64:67], v[178:181], v[210:213], v[64:67]
	s_barrier
	s_add_i32 s56, s48, s35
	v_lshl_add_u64 v[214:215], s[26:27], 0, v[146:147]
	s_mov_b32 m0, s56
	ds_read_b128 v[182:185], v169 offset:16384
	ds_read_b128 v[186:189], v169 offset:17408
	ds_read_b128 v[190:193], v169 offset:18432
	ds_read_b128 v[194:197], v169 offset:19456
	ds_read_b128 v[198:201], v169 offset:20480
	ds_read_b128 v[202:205], v169 offset:21504
	ds_read_b128 v[206:209], v169 offset:22528
	ds_read_b128 v[210:213], v169 offset:23552
	global_load_lds_dwordx4 v[214:215], off
	s_add_i32 m0, s56, 0x2000
	s_add_u32 s56, s26, 0x158000
	v_lshl_add_u64 v[216:217], s[26:27], 0, v[150:151]
	s_addc_u32 s57, s27, 0
	s_add_i32 s58, s49, s35
	global_load_lds_dwordx4 v[216:217], off
	v_lshl_add_u64 v[218:219], s[56:57], 0, v[146:147]
	s_mov_b32 m0, s58
	v_lshl_add_u64 v[220:221], s[28:29], 0, v[148:149]
	global_load_lds_dwordx4 v[218:219], off
	v_lshl_add_u64 v[218:219], s[56:57], 0, v[150:151]
	s_add_i32 m0, s58, 0x2000
	s_nop 0
	global_load_lds_dwordx4 v[218:219], off
	v_lshl_add_u64 v[218:219], s[28:29], 0, v[144:145]
	s_mov_b32 m0, s38
	s_nop 0
	global_load_lds_dwordx4 v[218:219], off
	s_mov_b32 m0, s39
	s_nop 0
	global_load_lds_dwordx4 v[220:221], off
	s_waitcnt vmcnt(8)
	s_waitcnt lgkmcnt(0)
	s_barrier
	v_mfma_i32_16x16x64_i8 v[60:63], v[104:107], v[182:185], v[60:63]
	v_mfma_i32_16x16x64_i8 v[56:59], v[112:115], v[182:185], v[56:59]
	v_mfma_i32_16x16x64_i8 v[44:47], v[104:107], v[190:193], v[44:47]
	v_mfma_i32_16x16x64_i8 v[40:43], v[112:115], v[190:193], v[40:43]
	v_mfma_i32_16x16x64_i8 v[28:31], v[104:107], v[198:201], v[28:31]
	v_mfma_i32_16x16x64_i8 v[24:27], v[112:115], v[198:201], v[24:27]
	v_mfma_i32_16x16x64_i8 v[12:15], v[104:107], v[206:209], v[12:15]
	v_mfma_i32_16x16x64_i8 v[8:11], v[112:115], v[206:209], v[8:11]
	v_mfma_i32_16x16x64_i8 v[60:63], v[108:111], v[186:189], v[60:63]
	v_mfma_i32_16x16x64_i8 v[56:59], v[120:123], v[186:189], v[56:59]
	v_mfma_i32_16x16x64_i8 v[44:47], v[108:111], v[194:197], v[44:47]
	v_mfma_i32_16x16x64_i8 v[40:43], v[120:123], v[194:197], v[40:43]
	v_mfma_i32_16x16x64_i8 v[28:31], v[108:111], v[202:205], v[28:31]
	v_mfma_i32_16x16x64_i8 v[24:27], v[120:123], v[202:205], v[24:27]
	v_mfma_i32_16x16x64_i8 v[12:15], v[108:111], v[210:213], v[12:15]
	v_mfma_i32_16x16x64_i8 v[8:11], v[120:123], v[210:213], v[8:11]
	v_mfma_i32_16x16x64_i8 v[52:55], v[158:161], v[182:185], v[52:55]
	v_mfma_i32_16x16x64_i8 v[48:51], v[174:177], v[182:185], v[48:51]
	v_mfma_i32_16x16x64_i8 v[36:39], v[158:161], v[190:193], v[36:39]
	v_mfma_i32_16x16x64_i8 v[32:35], v[174:177], v[190:193], v[32:35]
	v_mfma_i32_16x16x64_i8 v[20:23], v[158:161], v[198:201], v[20:23]
	v_mfma_i32_16x16x64_i8 v[16:19], v[174:177], v[198:201], v[16:19]
	v_mfma_i32_16x16x64_i8 v[4:7], v[158:161], v[206:209], v[4:7]
	v_mfma_i32_16x16x64_i8 v[0:3], v[174:177], v[206:209], v[0:3]
	v_mfma_i32_16x16x64_i8 v[52:55], v[170:173], v[186:189], v[52:55]
	v_mfma_i32_16x16x64_i8 v[48:51], v[178:181], v[186:189], v[48:51]
	v_mfma_i32_16x16x64_i8 v[36:39], v[170:173], v[194:197], v[36:39]
	v_mfma_i32_16x16x64_i8 v[32:35], v[178:181], v[194:197], v[32:35]
	v_mfma_i32_16x16x64_i8 v[20:23], v[170:173], v[202:205], v[20:23]
	v_mfma_i32_16x16x64_i8 v[16:19], v[178:181], v[202:205], v[16:19]
	v_mfma_i32_16x16x64_i8 v[4:7], v[170:173], v[210:213], v[4:7]
	v_mfma_i32_16x16x64_i8 v[0:3], v[178:181], v[210:213], v[0:3]
	s_barrier
	s_add_i32 s56, 0, 0x18000
	s_add_i32 s57, 0, 0x1c000
	v_add_u32_e32 v120, s56, v165
	v_add_u32_e32 v162, s57, v165
	ds_read_b128 v[104:107], v120
	ds_read_b128 v[108:111], v120 offset:1024
	ds_read_b128 v[112:115], v120 offset:2048
	ds_read_b128 v[120:123], v120 offset:3072
	ds_read_b128 v[158:161], v162
	ds_read_b128 v[170:173], v162 offset:1024
	ds_read_b128 v[174:177], v162 offset:2048
	ds_read_b128 v[178:181], v162 offset:3072
	s_add_u32 s28, s28, 0x158000
	s_addc_u32 s29, s29, 0
	s_mov_b32 m0, s40
	v_lshl_add_u64 v[222:223], s[28:29], 0, v[144:145]
	ds_read_b128 v[182:185], v169 offset:32768
	ds_read_b128 v[186:189], v169 offset:33792
	ds_read_b128 v[190:193], v169 offset:34816
	ds_read_b128 v[194:197], v169 offset:35840
	ds_read_b128 v[198:201], v169 offset:36864
	ds_read_b128 v[202:205], v169 offset:37888
	ds_read_b128 v[206:209], v169 offset:38912
	ds_read_b128 v[210:213], v169 offset:39936
	global_load_lds_dwordx4 v[222:223], off
	v_lshl_add_u64 v[222:223], s[28:29], 0, v[148:149]
	s_mov_b32 m0, s41
	s_nop 0
	global_load_lds_dwordx4 v[222:223], off
	s_waitcnt vmcnt(8)
	s_waitcnt lgkmcnt(0)
	s_barrier
	v_mfma_i32_16x16x64_i8 v[140:143], v[104:107], v[182:185], v[140:143]
	v_mfma_i32_16x16x64_i8 v[136:139], v[112:115], v[182:185], v[136:139]
	v_mfma_i32_16x16x64_i8 v[124:127], v[104:107], v[190:193], v[124:127]
	v_mfma_i32_16x16x64_i8 v[116:119], v[112:115], v[190:193], v[116:119]
	v_mfma_i32_16x16x64_i8 v[92:95], v[104:107], v[198:201], v[92:95]
	v_mfma_i32_16x16x64_i8 v[88:91], v[112:115], v[198:201], v[88:91]
	v_mfma_i32_16x16x64_i8 v[76:79], v[104:107], v[206:209], v[76:79]
	v_mfma_i32_16x16x64_i8 v[72:75], v[112:115], v[206:209], v[72:75]
	v_mfma_i32_16x16x64_i8 v[140:143], v[108:111], v[186:189], v[140:143]
	v_mfma_i32_16x16x64_i8 v[136:139], v[120:123], v[186:189], v[136:139]
	v_mfma_i32_16x16x64_i8 v[124:127], v[108:111], v[194:197], v[124:127]
	v_mfma_i32_16x16x64_i8 v[116:119], v[120:123], v[194:197], v[116:119]
	v_mfma_i32_16x16x64_i8 v[92:95], v[108:111], v[202:205], v[92:95]
	v_mfma_i32_16x16x64_i8 v[88:91], v[120:123], v[202:205], v[88:91]
	v_mfma_i32_16x16x64_i8 v[76:79], v[108:111], v[210:213], v[76:79]
	v_mfma_i32_16x16x64_i8 v[72:75], v[120:123], v[210:213], v[72:75]
	v_mfma_i32_16x16x64_i8 v[132:135], v[158:161], v[182:185], v[132:135]
	v_mfma_i32_16x16x64_i8 v[128:131], v[174:177], v[182:185], v[128:131]
	v_mfma_i32_16x16x64_i8 v[100:103], v[158:161], v[190:193], v[100:103]
	v_mfma_i32_16x16x64_i8 v[96:99], v[174:177], v[190:193], v[96:99]
	v_mfma_i32_16x16x64_i8 v[84:87], v[158:161], v[198:201], v[84:87]
	v_mfma_i32_16x16x64_i8 v[80:83], v[174:177], v[198:201], v[80:83]
	v_mfma_i32_16x16x64_i8 v[68:71], v[158:161], v[206:209], v[68:71]
	v_mfma_i32_16x16x64_i8 v[64:67], v[174:177], v[206:209], v[64:67]
	v_mfma_i32_16x16x64_i8 v[132:135], v[170:173], v[186:189], v[132:135]
	v_mfma_i32_16x16x64_i8 v[128:131], v[178:181], v[186:189], v[128:131]
	v_mfma_i32_16x16x64_i8 v[100:103], v[170:173], v[194:197], v[100:103]
	v_mfma_i32_16x16x64_i8 v[96:99], v[178:181], v[194:197], v[96:99]
	v_mfma_i32_16x16x64_i8 v[84:87], v[170:173], v[202:205], v[84:87]
	v_mfma_i32_16x16x64_i8 v[80:83], v[178:181], v[202:205], v[80:83]
	v_mfma_i32_16x16x64_i8 v[68:71], v[170:173], v[210:213], v[68:71]
	v_mfma_i32_16x16x64_i8 v[64:67], v[178:181], v[210:213], v[64:67]
	s_barrier
	s_add_i32 s28, s56, s35
	v_lshl_add_u64 v[214:215], v[214:215], 0, s[16:17]
	s_mov_b32 m0, s28
	ds_read_b128 v[182:185], v169 offset:49152
	ds_read_b128 v[186:189], v169 offset:50176
	ds_read_b128 v[190:193], v169 offset:51200
	ds_read_b128 v[194:197], v169 offset:52224
	ds_read_b128 v[198:201], v169 offset:53248
	ds_read_b128 v[202:205], v169 offset:54272
	ds_read_b128 v[206:209], v169 offset:55296
	ds_read_b128 v[210:213], v169 offset:56320
	global_load_lds_dwordx4 v[214:215], off
	s_add_i32 m0, s28, 0x2000
	s_add_u32 s26, s26, 0x158080
	v_lshl_add_u64 v[214:215], v[216:217], 0, s[16:17]
	s_addc_u32 s27, s27, 0
	s_add_i32 s28, s57, s35
	global_load_lds_dwordx4 v[214:215], off
	v_lshl_add_u64 v[214:215], s[26:27], 0, v[146:147]
	s_mov_b32 m0, s28
	s_nop 0
	global_load_lds_dwordx4 v[214:215], off
	v_lshl_add_u64 v[214:215], s[26:27], 0, v[150:151]
	s_add_i32 m0, s28, 0x2000
	s_nop 0
	global_load_lds_dwordx4 v[214:215], off
	v_lshl_add_u64 v[214:215], v[218:219], 0, s[16:17]
	s_mov_b32 m0, s42
	s_nop 0
	global_load_lds_dwordx4 v[214:215], off
	v_lshl_add_u64 v[214:215], v[220:221], 0, s[16:17]
	s_mov_b32 m0, s43
	s_nop 0
	global_load_lds_dwordx4 v[214:215], off
	s_waitcnt vmcnt(8)
	s_waitcnt lgkmcnt(0)
	s_barrier
	v_mfma_i32_16x16x64_i8 v[60:63], v[104:107], v[182:185], v[60:63]
	v_mfma_i32_16x16x64_i8 v[56:59], v[112:115], v[182:185], v[56:59]
	v_mfma_i32_16x16x64_i8 v[44:47], v[104:107], v[190:193], v[44:47]
	v_mfma_i32_16x16x64_i8 v[40:43], v[112:115], v[190:193], v[40:43]
	v_mfma_i32_16x16x64_i8 v[28:31], v[104:107], v[198:201], v[28:31]
	v_mfma_i32_16x16x64_i8 v[24:27], v[112:115], v[198:201], v[24:27]
	v_mfma_i32_16x16x64_i8 v[12:15], v[104:107], v[206:209], v[12:15]
	v_mfma_i32_16x16x64_i8 v[8:11], v[112:115], v[206:209], v[8:11]
	v_mfma_i32_16x16x64_i8 v[60:63], v[108:111], v[186:189], v[60:63]
	v_mfma_i32_16x16x64_i8 v[56:59], v[120:123], v[186:189], v[56:59]
	v_mfma_i32_16x16x64_i8 v[44:47], v[108:111], v[194:197], v[44:47]
	v_mfma_i32_16x16x64_i8 v[40:43], v[120:123], v[194:197], v[40:43]
	v_mfma_i32_16x16x64_i8 v[28:31], v[108:111], v[202:205], v[28:31]
	v_mfma_i32_16x16x64_i8 v[24:27], v[120:123], v[202:205], v[24:27]
	v_mfma_i32_16x16x64_i8 v[12:15], v[108:111], v[210:213], v[12:15]
	v_mfma_i32_16x16x64_i8 v[8:11], v[120:123], v[210:213], v[8:11]
	v_mfma_i32_16x16x64_i8 v[52:55], v[158:161], v[182:185], v[52:55]
	v_mfma_i32_16x16x64_i8 v[48:51], v[174:177], v[182:185], v[48:51]
	v_mfma_i32_16x16x64_i8 v[36:39], v[158:161], v[190:193], v[36:39]
	v_mfma_i32_16x16x64_i8 v[32:35], v[174:177], v[190:193], v[32:35]
	v_mfma_i32_16x16x64_i8 v[20:23], v[158:161], v[198:201], v[20:23]
	v_mfma_i32_16x16x64_i8 v[16:19], v[174:177], v[198:201], v[16:19]
	v_mfma_i32_16x16x64_i8 v[4:7], v[158:161], v[206:209], v[4:7]
	v_mfma_i32_16x16x64_i8 v[0:3], v[174:177], v[206:209], v[0:3]
	v_mfma_i32_16x16x64_i8 v[52:55], v[170:173], v[186:189], v[52:55]
	v_mfma_i32_16x16x64_i8 v[48:51], v[178:181], v[186:189], v[48:51]
	v_mfma_i32_16x16x64_i8 v[36:39], v[170:173], v[194:197], v[36:39]
	v_mfma_i32_16x16x64_i8 v[32:35], v[178:181], v[194:197], v[32:35]
	v_mfma_i32_16x16x64_i8 v[20:23], v[170:173], v[202:205], v[20:23]
	v_mfma_i32_16x16x64_i8 v[16:19], v[178:181], v[202:205], v[16:19]
	v_mfma_i32_16x16x64_i8 v[4:7], v[170:173], v[210:213], v[4:7]
	v_mfma_i32_16x16x64_i8 v[0:3], v[178:181], v[210:213], v[0:3]
	s_barrier
	s_add_i32 s55, s55, 2
	s_add_u32 s6, s6, 0x100
	s_addc_u32 s7, s7, 0
	s_add_u32 s8, s8, 0x100
	s_addc_u32 s9, s9, 0
	s_cmpk_gt_u32 s55, 0x53
	s_cbranch_scc0 .LBB0_1166
	s_setprio 0
	s_and_b64 vcc, exec, s[18:19]
	s_cbranch_vccz .LBB0_1169
	s_barrier
